# store coalescing in the row-sum exchange: per-panel buffer laid out [pn][row] so each workgroup writes one contiguous 1 KiB run of write-through stores (was 256 scattered 4-byte stores); readers use o
# speedup vs baseline: 1.0084x; 1.0053x over previous
; __device__ __forceinline__ float swap_add(float v) { auto rr = __builtin_amdgcn_permlane32_swap(__float_as_uint(v), __float_as_uint(v), false, false); return __uint_as_float(rr[0]) + __uint_as_float(rr[1]); }
;     __device__ __forceinline__ void exchange(const f32x4 (&acc)[2][2][4][2], const Unit& u, int e, int wr, int wc, int fr, int fq) const {
;     ...
;         for (int ai = 0; ai < 2; ++ai)
; #pragma unroll
;             for (int m = 0; m < 4; ++m) { float q = 0.f;
; #pragma unroll
;                 for (int bj = 0; bj < 2; ++bj)
; #pragma unroll
;                     for (int n = 0; n < 2; ++n) { const f32x4 v = acc[ai][bj][m][n]; q += (v[0] * v[0] + v[1] * v[1]) + (v[2] * v[2] + v[3] * v[3]); }
;                 q += __int_as_float(__builtin_amdgcn_ds_bpermute((lid ^ 16) << 2, __float_as_int(q))); q = swap_add(q);
;                 if (fq == 0) P[(ai * 128 + wr * 64 + m * 16 + fr) * 4 + wc] = q; }
.LBB0_68:
	v_mul_f32_e32 v142, v51, v51
	v_mul_f32_e32 v143, v53, v53
	v_fmac_f32_e32 v142, v50, v50
	v_fmac_f32_e32 v143, v52, v52
	v_add_f32_e32 v142, v142, v143
	v_mul_f32_e32 v143, v55, v55
	v_mul_f32_e32 v144, v57, v57
	v_fmac_f32_e32 v143, v54, v54
	v_fmac_f32_e32 v144, v56, v56
	v_add_f32_e32 v143, v143, v144
	v_add_f32_e32 v142, v142, v143
	v_mul_f32_e32 v143, v63, v63
	v_mul_f32_e32 v144, v65, v65
	v_fmac_f32_e32 v143, v62, v62
	v_fmac_f32_e32 v144, v64, v64
	v_add_f32_e32 v143, v143, v144
	v_add_f32_e32 v142, v142, v143
	v_mul_f32_e32 v143, v59, v59
	v_mul_f32_e32 v144, v61, v61
	v_fmac_f32_e32 v143, v58, v58
	v_fmac_f32_e32 v144, v60, v60
	v_add_f32_e32 v143, v143, v144
	v_add_f32_e32 v142, v142, v143
	ds_bpermute_b32 v143, v172, v142
	s_waitcnt lgkmcnt(0)
	v_add_f32_e32 v142, v142, v143
	v_mov_b32_e32 v143, v142
	s_nop 1
	v_permlane32_swap_b32_e32 v142, v143
	s_and_saveexec_b64 s[12:13], s[42:43]
	v_add_f32_e32 v142, v142, v143
	ds_write_b32 v201, v142
	s_or_b64 exec, exec, s[12:13]
	v_mul_f32_e32 v142, v75, v75
	v_mul_f32_e32 v143, v77, v77
	v_fmac_f32_e32 v142, v74, v74
	v_fmac_f32_e32 v143, v76, v76
	v_add_f32_e32 v142, v142, v143
	v_mul_f32_e32 v143, v79, v79
	v_mul_f32_e32 v144, v81, v81
	v_fmac_f32_e32 v143, v78, v78
	v_fmac_f32_e32 v144, v80, v80
	v_add_f32_e32 v143, v143, v144
	v_add_f32_e32 v142, v142, v143
	v_mul_f32_e32 v143, v95, v95
	v_mul_f32_e32 v144, v97, v97
	v_fmac_f32_e32 v143, v94, v94
	v_fmac_f32_e32 v144, v96, v96
	v_add_f32_e32 v143, v143, v144
	v_add_f32_e32 v142, v142, v143
	v_mul_f32_e32 v143, v91, v91
	v_mul_f32_e32 v144, v93, v93
	v_fmac_f32_e32 v143, v90, v90
	v_fmac_f32_e32 v144, v92, v92
	v_add_f32_e32 v143, v143, v144
	v_add_f32_e32 v142, v142, v143
	ds_bpermute_b32 v143, v172, v142
	s_waitcnt lgkmcnt(0)
	v_add_f32_e32 v142, v142, v143
	v_mov_b32_e32 v143, v142
	s_nop 1
	v_permlane32_swap_b32_e32 v142, v143
	s_and_saveexec_b64 s[12:13], s[42:43]
	v_add_f32_e32 v142, v142, v143
	ds_write_b32 v201, v142 offset:256
	s_or_b64 exec, exec, s[12:13]
	v_mul_f32_e32 v142, v99, v99
	v_mul_f32_e32 v143, v101, v101
	v_fmac_f32_e32 v142, v98, v98
	v_fmac_f32_e32 v143, v100, v100
	v_add_f32_e32 v142, v142, v143
	v_mul_f32_e32 v143, v103, v103
	v_mul_f32_e32 v144, v105, v105
	v_fmac_f32_e32 v143, v102, v102
	v_fmac_f32_e32 v144, v104, v104
	v_add_f32_e32 v143, v143, v144
	v_add_f32_e32 v142, v142, v143
	v_mul_f32_e32 v143, v119, v119
	v_mul_f32_e32 v144, v121, v121
	v_fmac_f32_e32 v143, v118, v118
	v_fmac_f32_e32 v144, v120, v120
	v_add_f32_e32 v143, v143, v144
	v_add_f32_e32 v142, v142, v143
	v_mul_f32_e32 v143, v115, v115
	v_mul_f32_e32 v144, v117, v117
	v_fmac_f32_e32 v143, v114, v114
	v_fmac_f32_e32 v144, v116, v116
	v_add_f32_e32 v143, v143, v144
	v_add_f32_e32 v142, v142, v143
	ds_bpermute_b32 v143, v172, v142
	s_waitcnt lgkmcnt(0)
	v_add_f32_e32 v142, v142, v143
	v_mov_b32_e32 v143, v142
	s_nop 1
	v_permlane32_swap_b32_e32 v142, v143
	s_and_saveexec_b64 s[12:13], s[42:43]
	v_add_f32_e32 v142, v142, v143
	ds_write_b32 v201, v142 offset:512
	s_or_b64 exec, exec, s[12:13]
	v_mul_f32_e32 v142, v127, v127
	v_mul_f32_e32 v143, v129, v129
	v_fmac_f32_e32 v142, v126, v126
	v_fmac_f32_e32 v143, v128, v128
	v_add_f32_e32 v142, v142, v143
	v_mul_f32_e32 v143, v123, v123
	v_mul_f32_e32 v144, v125, v125
	v_fmac_f32_e32 v143, v122, v122
	v_fmac_f32_e32 v144, v124, v124
	v_add_f32_e32 v143, v143, v144
	v_add_f32_e32 v142, v142, v143
	v_mul_f32_e32 v143, v111, v111
	v_mul_f32_e32 v144, v113, v113
	v_fmac_f32_e32 v143, v110, v110
	v_fmac_f32_e32 v144, v112, v112
	v_add_f32_e32 v143, v143, v144
	v_add_f32_e32 v142, v142, v143
	v_mul_f32_e32 v143, v107, v107
	v_mul_f32_e32 v144, v109, v109
	v_fmac_f32_e32 v143, v106, v106
	v_fmac_f32_e32 v144, v108, v108
	v_add_f32_e32 v143, v143, v144
	v_add_f32_e32 v142, v142, v143
	ds_bpermute_b32 v143, v172, v142
	s_waitcnt lgkmcnt(0)
	v_add_f32_e32 v142, v142, v143
	v_mov_b32_e32 v143, v142
	s_nop 1
	v_permlane32_swap_b32_e32 v142, v143
	s_and_saveexec_b64 s[12:13], s[42:43]
	v_add_f32_e32 v142, v142, v143
	ds_write_b32 v201, v142 offset:768
	s_or_b64 exec, exec, s[12:13]
	v_mul_f32_e32 v142, v87, v87
	v_mul_f32_e32 v143, v89, v89
	v_fmac_f32_e32 v142, v86, v86
	v_fmac_f32_e32 v143, v88, v88
	v_add_f32_e32 v142, v142, v143
	v_mul_f32_e32 v143, v83, v83
	v_mul_f32_e32 v144, v85, v85
	v_fmac_f32_e32 v143, v82, v82
	v_fmac_f32_e32 v144, v84, v84
	v_add_f32_e32 v143, v143, v144
	v_add_f32_e32 v142, v142, v143
	v_mul_f32_e32 v143, v71, v71
	v_mul_f32_e32 v144, v73, v73
	v_fmac_f32_e32 v143, v70, v70
	v_fmac_f32_e32 v144, v72, v72
	v_add_f32_e32 v143, v143, v144
	v_add_f32_e32 v142, v142, v143
	v_mul_f32_e32 v143, v67, v67
	v_mul_f32_e32 v144, v69, v69
	v_fmac_f32_e32 v143, v66, v66
	v_fmac_f32_e32 v144, v68, v68
	v_add_f32_e32 v143, v143, v144
	v_add_f32_e32 v142, v142, v143
	ds_bpermute_b32 v143, v172, v142
	s_waitcnt lgkmcnt(0)
; __device__ __forceinline__ float swap_add(float v) { auto rr = __builtin_amdgcn_permlane32_swap(__float_as_uint(v), __float_as_uint(v), false, false); return __uint_as_float(rr[0]) + __uint_as_float(rr[1]); }
;     __device__ __forceinline__ void exchange(const f32x4 (&acc)[2][2][4][2], const Unit& u, int e, int wr, int wc, int fr, int fq) const {
;     ...
;         for (int ai = 0; ai < 2; ++ai)
; #pragma unroll
;             for (int m = 0; m < 4; ++m) { float q = 0.f;
; #pragma unroll
;                 for (int bj = 0; bj < 2; ++bj)
; #pragma unroll
;                     for (int n = 0; n < 2; ++n) { const f32x4 v = acc[ai][bj][m][n]; q += (v[0] * v[0] + v[1] * v[1]) + (v[2] * v[2] + v[3] * v[3]); }
;                 q += __int_as_float(__builtin_amdgcn_ds_bpermute((lid ^ 16) << 2, __float_as_int(q))); q = swap_add(q);
;                 if (fq == 0) P[(ai * 128 + wr * 64 + m * 16 + fr) * 4 + wc] = q; }
;         __syncthreads();
;         float* xb = xbuf + (size_t)e * T * 4 + (size_t)u.pm * 256 * 4; unsigned* c = cnt + (e * 64 + u.pm) * 64;
;         if (tid < 256) { const float tot = (P[tid * 4] + P[tid * 4 + 1]) + (P[tid * 4 + 2] + P[tid * 4 + 3]);
;             __hip_atomic_store(xb + tid * 4 + u.pn, tot, __ATOMIC_RELAXED, __HIP_MEMORY_SCOPE_AGENT); }
	v_add_f32_e32 v142, v142, v143
	v_mov_b32_e32 v143, v142
	s_nop 1
	v_permlane32_swap_b32_e32 v142, v143
	s_and_saveexec_b64 s[12:13], s[42:43]
	v_add_f32_e32 v142, v142, v143
	ds_write_b32 v201, v142 offset:2048
	s_or_b64 exec, exec, s[12:13]
	v_mul_f32_e32 v142, v47, v47
	v_mul_f32_e32 v143, v49, v49
	v_fmac_f32_e32 v142, v46, v46
	v_fmac_f32_e32 v143, v48, v48
	v_add_f32_e32 v142, v142, v143
	v_mul_f32_e32 v143, v43, v43
	v_mul_f32_e32 v144, v45, v45
	v_fmac_f32_e32 v143, v42, v42
	v_fmac_f32_e32 v144, v44, v44
	v_add_f32_e32 v143, v143, v144
	v_add_f32_e32 v142, v142, v143
	v_mul_f32_e32 v143, v39, v39
	v_mul_f32_e32 v144, v41, v41
	v_fmac_f32_e32 v143, v38, v38
	v_fmac_f32_e32 v144, v40, v40
	v_add_f32_e32 v143, v143, v144
	v_add_f32_e32 v142, v142, v143
	v_mul_f32_e32 v143, v35, v35
	v_mul_f32_e32 v144, v37, v37
	v_fmac_f32_e32 v143, v34, v34
	v_fmac_f32_e32 v144, v36, v36
	v_add_f32_e32 v143, v143, v144
	v_add_f32_e32 v142, v142, v143
	ds_bpermute_b32 v143, v172, v142
	s_waitcnt lgkmcnt(0)
	v_add_f32_e32 v142, v142, v143
	v_mov_b32_e32 v143, v142
	s_nop 1
	v_permlane32_swap_b32_e32 v142, v143
	s_and_saveexec_b64 s[12:13], s[42:43]
	v_add_f32_e32 v142, v142, v143
	ds_write_b32 v201, v142 offset:2304
	s_or_b64 exec, exec, s[12:13]
	v_mul_f32_e32 v142, v31, v31
	v_mul_f32_e32 v143, v33, v33
	v_fmac_f32_e32 v142, v30, v30
	v_fmac_f32_e32 v143, v32, v32
	v_add_f32_e32 v142, v142, v143
	v_mul_f32_e32 v143, v27, v27
	v_mul_f32_e32 v144, v29, v29
	v_fmac_f32_e32 v143, v26, v26
	v_fmac_f32_e32 v144, v28, v28
	v_add_f32_e32 v143, v143, v144
	v_add_f32_e32 v142, v142, v143
	v_mul_f32_e32 v143, v23, v23
	v_mul_f32_e32 v144, v25, v25
	v_fmac_f32_e32 v143, v22, v22
	v_fmac_f32_e32 v144, v24, v24
	v_add_f32_e32 v143, v143, v144
	v_add_f32_e32 v142, v142, v143
	v_mul_f32_e32 v143, v19, v19
	v_mul_f32_e32 v144, v21, v21
	v_fmac_f32_e32 v143, v18, v18
	v_fmac_f32_e32 v144, v20, v20
	v_add_f32_e32 v143, v143, v144
	v_add_f32_e32 v142, v142, v143
	ds_bpermute_b32 v143, v172, v142
	s_waitcnt lgkmcnt(0)
	v_add_f32_e32 v142, v142, v143
	v_mov_b32_e32 v143, v142
	s_nop 1
	v_permlane32_swap_b32_e32 v142, v143
	s_and_saveexec_b64 s[12:13], s[42:43]
	v_add_f32_e32 v142, v142, v143
	ds_write_b32 v201, v142 offset:2560
	s_or_b64 exec, exec, s[12:13]
	v_mul_f32_e32 v142, v15, v15
	v_mul_f32_e32 v143, v17, v17
	v_fmac_f32_e32 v142, v14, v14
	v_fmac_f32_e32 v143, v16, v16
	v_add_f32_e32 v142, v142, v143
	v_mul_f32_e32 v143, v11, v11
	v_mul_f32_e32 v144, v13, v13
	v_fmac_f32_e32 v143, v10, v10
	v_fmac_f32_e32 v144, v12, v12
	v_add_f32_e32 v143, v143, v144
	v_add_f32_e32 v142, v142, v143
	v_mul_f32_e32 v143, v7, v7
	v_mul_f32_e32 v144, v9, v9
	v_fmac_f32_e32 v143, v6, v6
	v_fmac_f32_e32 v144, v8, v8
	v_add_f32_e32 v143, v143, v144
	v_add_f32_e32 v142, v142, v143
	v_mul_f32_e32 v143, v3, v3
	v_mul_f32_e32 v144, v5, v5
	v_fmac_f32_e32 v143, v2, v2
	v_fmac_f32_e32 v144, v4, v4
	v_add_f32_e32 v143, v143, v144
	v_add_f32_e32 v142, v142, v143
	ds_bpermute_b32 v143, v172, v142
	s_waitcnt lgkmcnt(0)
	v_add_f32_e32 v142, v142, v143
	v_mov_b32_e32 v143, v142
	s_nop 1
	v_permlane32_swap_b32_e32 v142, v143
	s_and_saveexec_b64 s[12:13], s[42:43]
	v_add_f32_e32 v142, v142, v143
	ds_write_b32 v201, v142 offset:2816
	s_or_b64 exec, exec, s[12:13]
	s_ashr_i32 s83, s82, 31
	s_lshl_b64 s[12:13], s[82:83], 12
	s_add_u32 s50, s36, s12
	s_addc_u32 s51, s39, s13
	v_lshl_add_u64 v[142:143], v[136:137], 0, s[50:51]
	s_waitcnt vmcnt(0) lgkmcnt(0)
	s_barrier
	s_and_saveexec_b64 s[50:51], s[44:45]
	s_cbranch_execz .LBB0_86
	ds_read_b128 v[144:147], v180
	s_ashr_i32 s79, s78, 31
	s_waitcnt lgkmcnt(0)
	v_mov_b32_e32 v148, v145
	v_mov_b32_e32 v149, v146
	v_mov_b32_e32 v145, v147
	v_pk_add_f32 v[144:145], v[148:149], v[144:145]
	v_lshl_add_u64 v[146:147], s[78:79], 4, 0
	v_lshl_add_u64 v[146:147], v[146:147], 4, 0
	v_lshl_add_u64 v[146:147], v[146:147], 2, v[142:143]
	v_pk_add_f32 v[144:145], v[144:145], v[144:145] op_sel:[0,1] op_sel_hi:[1,0]
	global_store_dword v[146:147], v144, off sc1

; #define LAS __attribute__((address_space(3)))
;     __device__ __forceinline__ void exchange(const f32x4 (&acc)[2][2][4][2], const Unit& u, int e, int wr, int wc, int fr, int fq) const {
;     ...
;         if (tid < 256) { float t4 = 0.f;
; #pragma unroll
;             for (int k = 0; k < 4; ++k) t4 += __hip_atomic_load(xb + tid * 4 + k, __ATOMIC_RELAXED, __HIP_MEMORY_SCOPE_AGENT);
;             S[tid] = 1.0f / sqrtf(t4 * (1.f / DM) + EPS); }
;         __syncthreads();
;     }
;     __device__ __forceinline__ void operator()(f32x4 (&acc)[2][2][4][2], const Unit& u, int wr, int wc, int fr, int fq) const {
;         const LAS float* S = (const LAS float*)(lds + EN_S);
;         const int col0 = u.pn * 256 + wc * 32 + 8 * fq;
;         exchange(acc, u, 0, wr, wc, fr, fq);
; #pragma unroll
;         for (int ai = 0; ai < 2; ++ai)
; #pragma unroll
;             for (int m = 0; m < 4; ++m) { const int rl = ai * 128 + wr * 64 + m * 16 + fr; const float r1 = S[rl]; const size_t off = (size_t)(u.pm * 256 + rl) * DM + col0;
; #pragma unroll
;                 for (int bj = 0; bj < 2; ++bj) { const f32x4 xa = *(const f32x4*)(xin + off + bj * 128), xb = *(const f32x4*)(xin + off + bj * 128 + 4);
;                     const f32x4 ga = *(const f32x4*)(gpost + col0 + bj * 128), gb = *(const f32x4*)(gpost + col0 + bj * 128 + 4);
;                     const f32x4 v0 = xa + acc[ai][bj][m][0] * r1 * ga, v1 = xb + acc[ai][bj][m][1] * r1 * gb;
;                     *(f32x4*)(xout + off + bj * 128) = v0; *(f32x4*)(xout + off + bj * 128 + 4) = v1; acc[ai][bj][m][0] = v0; acc[ai][bj][m][1] = v1; }
.LBB0_101:
	s_waitcnt vmcnt(0) lgkmcnt(0)
	s_waitcnt lgkmcnt(0)
	s_barrier
	s_and_saveexec_b64 s[84:85], s[44:45]
	s_cbranch_execz .LBB0_103
	global_load_dword v144, v[142:143], off sc1
	global_load_dword v145, v[142:143], off offset:1024 sc1
	global_load_dword v146, v[142:143], off offset:2048 sc1
	s_nop 0
	global_load_dword v142, v[142:143], off offset:3072 sc1
	s_mov_b32 s54, 0xf800000
	s_waitcnt vmcnt(3)
	v_add_f32_e32 v143, 0, v144
	s_waitcnt vmcnt(2)
	v_add_f32_e32 v143, v143, v145
	s_waitcnt vmcnt(1)
	v_add_f32_e32 v143, v143, v146
	s_waitcnt vmcnt(0)
	v_add_f32_e32 v142, v143, v142
	v_fmamk_f32 v142, v142, 0x3a800000, v193
	v_mul_f32_e32 v143, 0x4f800000, v142
	v_cmp_gt_f32_e32 vcc, s54, v142
	s_nop 1
	v_cndmask_b32_e32 v142, v142, v143, vcc
	v_sqrt_f32_e32 v143, v142
	s_nop 0
	v_add_u32_e32 v144, -1, v143
	v_add_u32_e32 v145, 1, v143
	v_fma_f32 v146, -v144, v143, v142
	v_fma_f32 v147, -v145, v143, v142
	v_cmp_ge_f32_e64 s[54:55], 0, v146
	s_nop 1
	v_cndmask_b32_e64 v143, v143, v144, s[54:55]
	v_cmp_lt_f32_e64 s[54:55], 0, v147
	s_nop 1
	v_cndmask_b32_e64 v143, v143, v145, s[54:55]
	v_mul_f32_e32 v144, 0x37800000, v143
	v_cndmask_b32_e32 v143, v143, v144, vcc
	v_cmp_class_f32_e32 vcc, v142, v194
	s_nop 1
	v_cndmask_b32_e32 v142, v143, v142, vcc
	v_div_scale_f32 v143, s[54:55], v142, v142, 1.0
	v_rcp_f32_e32 v144, v143
	v_div_scale_f32 v145, vcc, 1.0, v142, 1.0
	v_fma_f32 v146, -v143, v144, 1.0
	v_fmac_f32_e32 v144, v146, v144
	v_mul_f32_e32 v146, v145, v144
	v_fma_f32 v147, -v143, v146, v145
	v_fmac_f32_e32 v146, v147, v144
	v_fma_f32 v143, -v143, v146, v145
	v_div_fmas_f32 v143, v143, v144, v146
	v_div_fixup_f32 v142, v143, v142, 1.0
	ds_write_b32 v181, v142
.LBB0_103:
	s_or_b64 exec, exec, s[84:85]
	s_lshl_b32 s54, s82, 8
	v_add_u32_e32 v144, s54, v170
	v_lshl_or_b32 v142, s78, 8, v190
	v_ashrrev_i32_e32 v145, 31, v144
	v_ashrrev_i32_e32 v143, 31, v142
	v_lshlrev_b64 v[146:147], 12, v[144:145]
	v_lshl_add_u64 v[146:147], s[34:35], 0, v[146:147]
	v_lshlrev_b64 v[158:159], 2, v[142:143]
	v_lshl_add_u64 v[160:161], v[146:147], 0, v[158:159]
	v_lshl_add_u64 v[154:155], s[52:53], 0, v[158:159]
	global_load_dwordx4 v[218:221], v[154:155], off
	global_load_dwordx4 v[222:225], v[154:155], off offset:16
	global_load_dwordx4 v[226:229], v[154:155], off offset:512
	global_load_dwordx4 v[230:233], v[154:155], off offset:528
	s_waitcnt lgkmcnt(0)
	s_barrier
	s_andn2_b64 vcc, exec, s[62:63]
	ds_read_b32 v154, v182
	global_load_dwordx4 v[202:205], v[160:161], off offset:16
	global_load_dwordx4 v[206:209], v[160:161], off
	global_load_dwordx4 v[210:213], v[160:161], off offset:528
	global_load_dwordx4 v[214:217], v[160:161], off offset:512
	v_add_u32_e32 v164, s54, v173
	v_ashrrev_i32_e32 v165, 31, v164
	v_lshlrev_b64 v[164:165], 12, v[164:165]
	v_lshl_add_u64 v[164:165], s[34:35], 0, v[164:165]
	v_lshl_add_u64 v[162:163], v[164:165], 0, v[158:159]
	ds_read_b32 v156, v183
	global_load_dwordx4 v[234:237], v[162:163], off offset:16
	global_load_dwordx4 v[238:241], v[162:163], off
	global_load_dwordx4 v[146:149], v[162:163], off offset:528
	global_load_dwordx4 v[150:153], v[162:163], off offset:512
	s_waitcnt lgkmcnt(1)
	v_pk_mul_f32 v[50:51], v[50:51], v[154:155] op_sel_hi:[1,0]
	v_pk_mul_f32 v[52:53], v[52:53], v[154:155] op_sel_hi:[1,0]
	v_pk_mul_f32 v[54:55], v[54:55], v[154:155] op_sel_hi:[1,0]
	v_pk_mul_f32 v[56:57], v[56:57], v[154:155] op_sel_hi:[1,0]
	v_pk_mul_f32 v[62:63], v[62:63], v[154:155] op_sel_hi:[1,0]
	v_pk_mul_f32 v[64:65], v[64:65], v[154:155] op_sel_hi:[1,0]
	v_pk_mul_f32 v[58:59], v[58:59], v[154:155] op_sel_hi:[1,0]
	v_pk_mul_f32 v[60:61], v[60:61], v[154:155] op_sel_hi:[1,0]
	s_waitcnt vmcnt(4)
	v_pk_fma_f32 v[54:55], v[54:55], v[222:223], v[202:203]
	v_pk_fma_f32 v[56:57], v[56:57], v[224:225], v[204:205]
	v_pk_fma_f32 v[50:51], v[50:51], v[218:219], v[206:207]
	v_pk_fma_f32 v[52:53], v[52:53], v[220:221], v[208:209]
	v_pk_fma_f32 v[58:59], v[58:59], v[230:231], v[210:211]
	v_pk_fma_f32 v[60:61], v[60:61], v[232:233], v[212:213]
	v_pk_fma_f32 v[62:63], v[62:63], v[226:227], v[214:215]
	v_pk_fma_f32 v[64:65], v[64:65], v[228:229], v[216:217]
	global_store_dwordx4 v[160:161], v[50:53], off
	global_store_dwordx4 v[160:161], v[54:57], off offset:16
	global_store_dwordx4 v[160:161], v[62:65], off offset:512
	global_store_dwordx4 v[160:161], v[58:61], off offset:528
	v_add_u32_e32 v164, s54, v174
	v_ashrrev_i32_e32 v165, 31, v164
	v_lshlrev_b64 v[164:165], 12, v[164:165]
	v_lshl_add_u64 v[164:165], s[34:35], 0, v[164:165]
	v_lshl_add_u64 v[160:161], v[164:165], 0, v[158:159]
	ds_read_b32 v154, v184
	global_load_dwordx4 v[202:205], v[160:161], off offset:16
	global_load_dwordx4 v[206:209], v[160:161], off
	global_load_dwordx4 v[210:213], v[160:161], off offset:528
	global_load_dwordx4 v[214:217], v[160:161], off offset:512
	s_waitcnt lgkmcnt(1)
	v_pk_mul_f32 v[74:75], v[74:75], v[156:157] op_sel_hi:[1,0]
	v_pk_mul_f32 v[76:77], v[76:77], v[156:157] op_sel_hi:[1,0]
	v_pk_mul_f32 v[78:79], v[78:79], v[156:157] op_sel_hi:[1,0]
	v_pk_mul_f32 v[80:81], v[80:81], v[156:157] op_sel_hi:[1,0]
	v_pk_mul_f32 v[94:95], v[94:95], v[156:157] op_sel_hi:[1,0]
	v_pk_mul_f32 v[96:97], v[96:97], v[156:157] op_sel_hi:[1,0]
	v_pk_mul_f32 v[90:91], v[90:91], v[156:157] op_sel_hi:[1,0]
	v_pk_mul_f32 v[92:93], v[92:93], v[156:157] op_sel_hi:[1,0]
	s_waitcnt vmcnt(8)
;     __device__ __forceinline__ void operator()(f32x4 (&acc)[2][2][4][2], const Unit& u, int wr, int wc, int fr, int fq) const {
;     ...
; #pragma unroll
;         for (int ai = 0; ai < 2; ++ai)
; #pragma unroll
;             for (int m = 0; m < 4; ++m) { const int rl = ai * 128 + wr * 64 + m * 16 + fr; const float r1 = S[rl]; const size_t off = (size_t)(u.pm * 256 + rl) * DM + col0;
; #pragma unroll
;                 for (int bj = 0; bj < 2; ++bj) { const f32x4 xa = *(const f32x4*)(xin + off + bj * 128), xb = *(const f32x4*)(xin + off + bj * 128 + 4);
;                     const f32x4 ga = *(const f32x4*)(gpost + col0 + bj * 128), gb = *(const f32x4*)(gpost + col0 + bj * 128 + 4);
;                     const f32x4 v0 = xa + acc[ai][bj][m][0] * r1 * ga, v1 = xb + acc[ai][bj][m][1] * r1 * gb;
;                     *(f32x4*)(xout + off + bj * 128) = v0; *(f32x4*)(xout + off + bj * 128 + 4) = v1; acc[ai][bj][m][0] = v0; acc[ai][bj][m][1] = v1; }
;                 asm volatile("" ::: "memory"); }
	v_pk_fma_f32 v[78:79], v[78:79], v[222:223], v[234:235]
	v_pk_fma_f32 v[80:81], v[80:81], v[224:225], v[236:237]
	v_pk_fma_f32 v[74:75], v[74:75], v[218:219], v[238:239]
	v_pk_fma_f32 v[76:77], v[76:77], v[220:221], v[240:241]
	v_pk_fma_f32 v[90:91], v[90:91], v[230:231], v[146:147]
	v_pk_fma_f32 v[92:93], v[92:93], v[232:233], v[148:149]
	v_pk_fma_f32 v[94:95], v[94:95], v[226:227], v[150:151]
	v_pk_fma_f32 v[96:97], v[96:97], v[228:229], v[152:153]
	global_store_dwordx4 v[162:163], v[74:77], off
	global_store_dwordx4 v[162:163], v[78:81], off offset:16
	global_store_dwordx4 v[162:163], v[94:97], off offset:512
	global_store_dwordx4 v[162:163], v[90:93], off offset:528
	v_add_u32_e32 v164, s54, v175
	v_ashrrev_i32_e32 v165, 31, v164
	v_lshlrev_b64 v[164:165], 12, v[164:165]
	v_lshl_add_u64 v[164:165], s[34:35], 0, v[164:165]
	v_lshl_add_u64 v[162:163], v[164:165], 0, v[158:159]
	ds_read_b32 v156, v185
	global_load_dwordx4 v[234:237], v[162:163], off offset:16
	global_load_dwordx4 v[238:241], v[162:163], off
	global_load_dwordx4 v[146:149], v[162:163], off offset:528
	global_load_dwordx4 v[150:153], v[162:163], off offset:512
	s_waitcnt lgkmcnt(1)
	v_pk_mul_f32 v[98:99], v[98:99], v[154:155] op_sel_hi:[1,0]
	v_pk_mul_f32 v[100:101], v[100:101], v[154:155] op_sel_hi:[1,0]
	v_pk_mul_f32 v[102:103], v[102:103], v[154:155] op_sel_hi:[1,0]
	v_pk_mul_f32 v[104:105], v[104:105], v[154:155] op_sel_hi:[1,0]
	v_pk_mul_f32 v[118:119], v[118:119], v[154:155] op_sel_hi:[1,0]
	v_pk_mul_f32 v[120:121], v[120:121], v[154:155] op_sel_hi:[1,0]
	v_pk_mul_f32 v[114:115], v[114:115], v[154:155] op_sel_hi:[1,0]
	v_pk_mul_f32 v[116:117], v[116:117], v[154:155] op_sel_hi:[1,0]
	s_waitcnt vmcnt(8)
	v_pk_fma_f32 v[102:103], v[102:103], v[222:223], v[202:203]
	v_pk_fma_f32 v[104:105], v[104:105], v[224:225], v[204:205]
	v_pk_fma_f32 v[98:99], v[98:99], v[218:219], v[206:207]
	v_pk_fma_f32 v[100:101], v[100:101], v[220:221], v[208:209]
	v_pk_fma_f32 v[114:115], v[114:115], v[230:231], v[210:211]
	v_pk_fma_f32 v[116:117], v[116:117], v[232:233], v[212:213]
	v_pk_fma_f32 v[118:119], v[118:119], v[226:227], v[214:215]
	v_pk_fma_f32 v[120:121], v[120:121], v[228:229], v[216:217]
	global_store_dwordx4 v[160:161], v[98:101], off
	global_store_dwordx4 v[160:161], v[102:105], off offset:16
	global_store_dwordx4 v[160:161], v[118:121], off offset:512
	global_store_dwordx4 v[160:161], v[114:117], off offset:528
	v_add_u32_e32 v164, s54, v176
	v_ashrrev_i32_e32 v165, 31, v164
	v_lshlrev_b64 v[164:165], 12, v[164:165]
	v_lshl_add_u64 v[164:165], s[34:35], 0, v[164:165]
	v_lshl_add_u64 v[160:161], v[164:165], 0, v[158:159]
	ds_read_b32 v154, v186
	global_load_dwordx4 v[202:205], v[160:161], off offset:16
	global_load_dwordx4 v[206:209], v[160:161], off
	global_load_dwordx4 v[210:213], v[160:161], off offset:528
	global_load_dwordx4 v[214:217], v[160:161], off offset:512
	s_waitcnt lgkmcnt(1)
	v_pk_mul_f32 v[126:127], v[126:127], v[156:157] op_sel_hi:[1,0]
	v_pk_mul_f32 v[128:129], v[128:129], v[156:157] op_sel_hi:[1,0]
	v_pk_mul_f32 v[122:123], v[122:123], v[156:157] op_sel_hi:[1,0]
	v_pk_mul_f32 v[124:125], v[124:125], v[156:157] op_sel_hi:[1,0]
	v_pk_mul_f32 v[110:111], v[110:111], v[156:157] op_sel_hi:[1,0]
	v_pk_mul_f32 v[112:113], v[112:113], v[156:157] op_sel_hi:[1,0]
	v_pk_mul_f32 v[106:107], v[106:107], v[156:157] op_sel_hi:[1,0]
	v_pk_mul_f32 v[108:109], v[108:109], v[156:157] op_sel_hi:[1,0]
	s_waitcnt vmcnt(8)
	v_pk_fma_f32 v[122:123], v[122:123], v[222:223], v[234:235]
	v_pk_fma_f32 v[124:125], v[124:125], v[224:225], v[236:237]
	v_pk_fma_f32 v[126:127], v[126:127], v[218:219], v[238:239]
	v_pk_fma_f32 v[128:129], v[128:129], v[220:221], v[240:241]
	v_pk_fma_f32 v[106:107], v[106:107], v[230:231], v[146:147]
	v_pk_fma_f32 v[108:109], v[108:109], v[232:233], v[148:149]
	v_pk_fma_f32 v[110:111], v[110:111], v[226:227], v[150:151]
	v_pk_fma_f32 v[112:113], v[112:113], v[228:229], v[152:153]
	global_store_dwordx4 v[162:163], v[126:129], off
	global_store_dwordx4 v[162:163], v[122:125], off offset:16
	global_store_dwordx4 v[162:163], v[110:113], off offset:512
	global_store_dwordx4 v[162:163], v[106:109], off offset:528
	v_add_u32_e32 v164, s54, v177
	v_ashrrev_i32_e32 v165, 31, v164
	v_lshlrev_b64 v[164:165], 12, v[164:165]
	v_lshl_add_u64 v[164:165], s[34:35], 0, v[164:165]
	v_lshl_add_u64 v[162:163], v[164:165], 0, v[158:159]
	ds_read_b32 v156, v187
	global_load_dwordx4 v[234:237], v[162:163], off offset:16
	global_load_dwordx4 v[238:241], v[162:163], off
	global_load_dwordx4 v[146:149], v[162:163], off offset:528
	global_load_dwordx4 v[150:153], v[162:163], off offset:512
	s_waitcnt lgkmcnt(1)
	v_pk_mul_f32 v[86:87], v[86:87], v[154:155] op_sel_hi:[1,0]
	v_pk_mul_f32 v[88:89], v[88:89], v[154:155] op_sel_hi:[1,0]
	v_pk_mul_f32 v[82:83], v[82:83], v[154:155] op_sel_hi:[1,0]
	v_pk_mul_f32 v[84:85], v[84:85], v[154:155] op_sel_hi:[1,0]
	v_pk_mul_f32 v[70:71], v[70:71], v[154:155] op_sel_hi:[1,0]
	v_pk_mul_f32 v[72:73], v[72:73], v[154:155] op_sel_hi:[1,0]
	v_pk_mul_f32 v[66:67], v[66:67], v[154:155] op_sel_hi:[1,0]
	v_pk_mul_f32 v[68:69], v[68:69], v[154:155] op_sel_hi:[1,0]
	s_waitcnt vmcnt(8)
;     __device__ __forceinline__ void operator()(f32x4 (&acc)[2][2][4][2], const Unit& u, int wr, int wc, int fr, int fq) const {
;     ...
; #pragma unroll
;         for (int ai = 0; ai < 2; ++ai)
; #pragma unroll
;             for (int m = 0; m < 4; ++m) { const int rl = ai * 128 + wr * 64 + m * 16 + fr; const float r1 = S[rl]; const size_t off = (size_t)(u.pm * 256 + rl) * DM + col0;
; #pragma unroll
;                 for (int bj = 0; bj < 2; ++bj) { const f32x4 xa = *(const f32x4*)(xin + off + bj * 128), xb = *(const f32x4*)(xin + off + bj * 128 + 4);
;                     const f32x4 ga = *(const f32x4*)(gpost + col0 + bj * 128), gb = *(const f32x4*)(gpost + col0 + bj * 128 + 4);
;                     const f32x4 v0 = xa + acc[ai][bj][m][0] * r1 * ga, v1 = xb + acc[ai][bj][m][1] * r1 * gb;
;                     *(f32x4*)(xout + off + bj * 128) = v0; *(f32x4*)(xout + off + bj * 128 + 4) = v1; acc[ai][bj][m][0] = v0; acc[ai][bj][m][1] = v1; }
;                 asm volatile("" ::: "memory"); }
;         if (gnext) {
;             exchange(acc, u, 1, wr, wc, fr, fq);
	v_pk_fma_f32 v[82:83], v[82:83], v[222:223], v[202:203]
	v_pk_fma_f32 v[84:85], v[84:85], v[224:225], v[204:205]
	v_pk_fma_f32 v[86:87], v[86:87], v[218:219], v[206:207]
	v_pk_fma_f32 v[88:89], v[88:89], v[220:221], v[208:209]
	v_pk_fma_f32 v[66:67], v[66:67], v[230:231], v[210:211]
	v_pk_fma_f32 v[68:69], v[68:69], v[232:233], v[212:213]
	v_pk_fma_f32 v[70:71], v[70:71], v[226:227], v[214:215]
	v_pk_fma_f32 v[72:73], v[72:73], v[228:229], v[216:217]
	global_store_dwordx4 v[160:161], v[86:89], off
	global_store_dwordx4 v[160:161], v[82:85], off offset:16
	global_store_dwordx4 v[160:161], v[70:73], off offset:512
	global_store_dwordx4 v[160:161], v[66:69], off offset:528
	v_add_u32_e32 v164, s54, v178
	v_ashrrev_i32_e32 v165, 31, v164
	v_lshlrev_b64 v[164:165], 12, v[164:165]
	v_lshl_add_u64 v[164:165], s[34:35], 0, v[164:165]
	v_lshl_add_u64 v[160:161], v[164:165], 0, v[158:159]
	ds_read_b32 v154, v188
	global_load_dwordx4 v[202:205], v[160:161], off offset:16
	global_load_dwordx4 v[206:209], v[160:161], off
	global_load_dwordx4 v[210:213], v[160:161], off offset:528
	global_load_dwordx4 v[214:217], v[160:161], off offset:512
	s_waitcnt lgkmcnt(1)
	v_pk_mul_f32 v[46:47], v[46:47], v[156:157] op_sel_hi:[1,0]
	v_pk_mul_f32 v[48:49], v[48:49], v[156:157] op_sel_hi:[1,0]
	v_pk_mul_f32 v[42:43], v[42:43], v[156:157] op_sel_hi:[1,0]
	v_pk_mul_f32 v[44:45], v[44:45], v[156:157] op_sel_hi:[1,0]
	v_pk_mul_f32 v[38:39], v[38:39], v[156:157] op_sel_hi:[1,0]
	v_pk_mul_f32 v[40:41], v[40:41], v[156:157] op_sel_hi:[1,0]
	v_pk_mul_f32 v[34:35], v[34:35], v[156:157] op_sel_hi:[1,0]
	v_pk_mul_f32 v[36:37], v[36:37], v[156:157] op_sel_hi:[1,0]
	s_waitcnt vmcnt(8)
	v_pk_fma_f32 v[42:43], v[42:43], v[222:223], v[234:235]
	v_pk_fma_f32 v[44:45], v[44:45], v[224:225], v[236:237]
	v_pk_fma_f32 v[46:47], v[46:47], v[218:219], v[238:239]
	v_pk_fma_f32 v[48:49], v[48:49], v[220:221], v[240:241]
	v_pk_fma_f32 v[34:35], v[34:35], v[230:231], v[146:147]
	v_pk_fma_f32 v[36:37], v[36:37], v[232:233], v[148:149]
	v_pk_fma_f32 v[38:39], v[38:39], v[226:227], v[150:151]
	v_pk_fma_f32 v[40:41], v[40:41], v[228:229], v[152:153]
	global_store_dwordx4 v[162:163], v[46:49], off
	global_store_dwordx4 v[162:163], v[42:45], off offset:16
	global_store_dwordx4 v[162:163], v[38:41], off offset:512
	global_store_dwordx4 v[162:163], v[34:37], off offset:528
	v_add_u32_e32 v164, s54, v179
	v_ashrrev_i32_e32 v165, 31, v164
	v_lshlrev_b64 v[164:165], 12, v[164:165]
	v_lshl_add_u64 v[164:165], s[34:35], 0, v[164:165]
	v_lshl_add_u64 v[162:163], v[164:165], 0, v[158:159]
	ds_read_b32 v156, v189
	global_load_dwordx4 v[234:237], v[162:163], off offset:16
	global_load_dwordx4 v[238:241], v[162:163], off
	global_load_dwordx4 v[146:149], v[162:163], off offset:528
	global_load_dwordx4 v[150:153], v[162:163], off offset:512
	s_waitcnt lgkmcnt(1)
	v_pk_mul_f32 v[30:31], v[30:31], v[154:155] op_sel_hi:[1,0]
	v_pk_mul_f32 v[32:33], v[32:33], v[154:155] op_sel_hi:[1,0]
	v_pk_mul_f32 v[26:27], v[26:27], v[154:155] op_sel_hi:[1,0]
	v_pk_mul_f32 v[28:29], v[28:29], v[154:155] op_sel_hi:[1,0]
	v_pk_mul_f32 v[22:23], v[22:23], v[154:155] op_sel_hi:[1,0]
	v_pk_mul_f32 v[24:25], v[24:25], v[154:155] op_sel_hi:[1,0]
	v_pk_mul_f32 v[18:19], v[18:19], v[154:155] op_sel_hi:[1,0]
	v_pk_mul_f32 v[20:21], v[20:21], v[154:155] op_sel_hi:[1,0]
	s_waitcnt vmcnt(8)
	v_pk_fma_f32 v[26:27], v[26:27], v[222:223], v[202:203]
	v_pk_fma_f32 v[28:29], v[28:29], v[224:225], v[204:205]
	v_pk_fma_f32 v[30:31], v[30:31], v[218:219], v[206:207]
	v_pk_fma_f32 v[32:33], v[32:33], v[220:221], v[208:209]
	v_pk_fma_f32 v[18:19], v[18:19], v[230:231], v[210:211]
	v_pk_fma_f32 v[20:21], v[20:21], v[232:233], v[212:213]
	v_pk_fma_f32 v[22:23], v[22:23], v[226:227], v[214:215]
	v_pk_fma_f32 v[24:25], v[24:25], v[228:229], v[216:217]
	global_store_dwordx4 v[160:161], v[30:33], off
	global_store_dwordx4 v[160:161], v[26:29], off offset:16
	global_store_dwordx4 v[160:161], v[22:25], off offset:512
	global_store_dwordx4 v[160:161], v[18:21], off offset:528
	s_waitcnt lgkmcnt(0)
	v_pk_mul_f32 v[14:15], v[14:15], v[156:157] op_sel_hi:[1,0]
	v_pk_mul_f32 v[16:17], v[16:17], v[156:157] op_sel_hi:[1,0]
	v_pk_mul_f32 v[10:11], v[10:11], v[156:157] op_sel_hi:[1,0]
	v_pk_mul_f32 v[12:13], v[12:13], v[156:157] op_sel_hi:[1,0]
	v_pk_mul_f32 v[6:7], v[6:7], v[156:157] op_sel_hi:[1,0]
	v_pk_mul_f32 v[8:9], v[8:9], v[156:157] op_sel_hi:[1,0]
	v_pk_mul_f32 v[2:3], v[2:3], v[156:157] op_sel_hi:[1,0]
	v_pk_mul_f32 v[4:5], v[4:5], v[156:157] op_sel_hi:[1,0]
	s_waitcnt vmcnt(4)
	v_pk_fma_f32 v[10:11], v[10:11], v[222:223], v[234:235]
	v_pk_fma_f32 v[12:13], v[12:13], v[224:225], v[236:237]
	v_pk_fma_f32 v[14:15], v[14:15], v[218:219], v[238:239]
	v_pk_fma_f32 v[16:17], v[16:17], v[220:221], v[240:241]
	v_pk_fma_f32 v[2:3], v[2:3], v[230:231], v[146:147]
	v_pk_fma_f32 v[4:5], v[4:5], v[232:233], v[148:149]
	v_pk_fma_f32 v[6:7], v[6:7], v[226:227], v[150:151]
	v_pk_fma_f32 v[8:9], v[8:9], v[228:229], v[152:153]
	global_store_dwordx4 v[162:163], v[14:17], off
	global_store_dwordx4 v[162:163], v[10:13], off offset:16
	global_store_dwordx4 v[162:163], v[6:9], off offset:512
	global_store_dwordx4 v[162:163], v[2:5], off offset:528
	v_add_u32_e32 v146, s54, v173
	v_ashrrev_i32_e32 v147, 31, v146
	v_add_u32_e32 v148, s54, v174
	v_ashrrev_i32_e32 v149, 31, v148
	v_add_u32_e32 v150, s54, v175
	v_ashrrev_i32_e32 v151, 31, v150
	v_add_u32_e32 v152, s54, v176
	v_ashrrev_i32_e32 v153, 31, v152
	v_add_u32_e32 v156, s54, v177
	v_ashrrev_i32_e32 v157, 31, v156
	v_add_u32_e32 v166, s54, v178
	v_ashrrev_i32_e32 v167, 31, v166
	v_add_u32_e32 v168, s54, v179
	v_ashrrev_i32_e32 v169, 31, v168
	s_cbranch_vccnz .LBB0_140
; __device__ __forceinline__ float swap_add(float v) { auto rr = __builtin_amdgcn_permlane32_swap(__float_as_uint(v), __float_as_uint(v), false, false); return __uint_as_float(rr[0]) + __uint_as_float(rr[1]); }
;     __device__ __forceinline__ void exchange(const f32x4 (&acc)[2][2][4][2], const Unit& u, int e, int wr, int wc, int fr, int fq) const {
;     ...
;         for (int ai = 0; ai < 2; ++ai)
; #pragma unroll
;             for (int m = 0; m < 4; ++m) { float q = 0.f;
; #pragma unroll
;                 for (int bj = 0; bj < 2; ++bj)
; #pragma unroll
;                     for (int n = 0; n < 2; ++n) { const f32x4 v = acc[ai][bj][m][n]; q += (v[0] * v[0] + v[1] * v[1]) + (v[2] * v[2] + v[3] * v[3]); }
;                 q += __int_as_float(__builtin_amdgcn_ds_bpermute((lid ^ 16) << 2, __float_as_int(q))); q = swap_add(q);
;                 if (fq == 0) P[(ai * 128 + wr * 64 + m * 16 + fr) * 4 + wc] = q; }
	v_mul_f32_e32 v154, v51, v51
	v_mul_f32_e32 v155, v53, v53
	v_fmac_f32_e32 v154, v50, v50
	v_fmac_f32_e32 v155, v52, v52
	v_add_f32_e32 v154, v154, v155
	v_mul_f32_e32 v155, v55, v55
	v_mul_f32_e32 v158, v57, v57
	v_fmac_f32_e32 v155, v54, v54
	v_fmac_f32_e32 v158, v56, v56
	v_add_f32_e32 v155, v155, v158
	v_add_f32_e32 v154, v154, v155
	v_mul_f32_e32 v155, v63, v63
	v_mul_f32_e32 v158, v65, v65
	v_fmac_f32_e32 v155, v62, v62
	v_fmac_f32_e32 v158, v64, v64
	v_add_f32_e32 v155, v155, v158
	v_add_f32_e32 v154, v154, v155
	v_mul_f32_e32 v155, v59, v59
	v_mul_f32_e32 v158, v61, v61
	v_fmac_f32_e32 v155, v58, v58
	v_fmac_f32_e32 v158, v60, v60
	v_add_f32_e32 v155, v155, v158
	v_add_f32_e32 v154, v154, v155
	ds_bpermute_b32 v155, v172, v154
	s_waitcnt lgkmcnt(0)
	v_add_f32_e32 v154, v154, v155
	v_mov_b32_e32 v155, v154
	s_nop 1
	v_permlane32_swap_b32_e32 v154, v155
	s_and_saveexec_b64 s[54:55], s[42:43]
	v_add_f32_e32 v154, v154, v155
	ds_write_b32 v201, v154
	s_or_b64 exec, exec, s[54:55]
	v_mul_f32_e32 v154, v75, v75
	v_mul_f32_e32 v155, v77, v77
	v_fmac_f32_e32 v154, v74, v74
	v_fmac_f32_e32 v155, v76, v76
	v_add_f32_e32 v154, v154, v155
	v_mul_f32_e32 v155, v79, v79
	v_mul_f32_e32 v158, v81, v81
	v_fmac_f32_e32 v155, v78, v78
	v_fmac_f32_e32 v158, v80, v80
	v_add_f32_e32 v155, v155, v158
	v_add_f32_e32 v154, v154, v155
	v_mul_f32_e32 v155, v95, v95
	v_mul_f32_e32 v158, v97, v97
	v_fmac_f32_e32 v155, v94, v94
	v_fmac_f32_e32 v158, v96, v96
	v_add_f32_e32 v155, v155, v158
	v_add_f32_e32 v154, v154, v155
	v_mul_f32_e32 v155, v91, v91
	v_mul_f32_e32 v158, v93, v93
	v_fmac_f32_e32 v155, v90, v90
	v_fmac_f32_e32 v158, v92, v92
	v_add_f32_e32 v155, v155, v158
	v_add_f32_e32 v154, v154, v155
	ds_bpermute_b32 v155, v172, v154
	s_waitcnt lgkmcnt(0)
	v_add_f32_e32 v154, v154, v155
	v_mov_b32_e32 v155, v154
	s_nop 1
	v_permlane32_swap_b32_e32 v154, v155
	s_and_saveexec_b64 s[54:55], s[42:43]
	v_add_f32_e32 v154, v154, v155
	ds_write_b32 v201, v154 offset:256
	s_or_b64 exec, exec, s[54:55]
	v_mul_f32_e32 v154, v99, v99
	v_mul_f32_e32 v155, v101, v101
	v_fmac_f32_e32 v154, v98, v98
	v_fmac_f32_e32 v155, v100, v100
	v_add_f32_e32 v154, v154, v155
	v_mul_f32_e32 v155, v103, v103
	v_mul_f32_e32 v158, v105, v105
	v_fmac_f32_e32 v155, v102, v102
	v_fmac_f32_e32 v158, v104, v104
	v_add_f32_e32 v155, v155, v158
	v_add_f32_e32 v154, v154, v155
	v_mul_f32_e32 v155, v119, v119
	v_mul_f32_e32 v158, v121, v121
	v_fmac_f32_e32 v155, v118, v118
	v_fmac_f32_e32 v158, v120, v120
	v_add_f32_e32 v155, v155, v158
	v_add_f32_e32 v154, v154, v155
	v_mul_f32_e32 v155, v115, v115
	v_mul_f32_e32 v158, v117, v117
	v_fmac_f32_e32 v155, v114, v114
	v_fmac_f32_e32 v158, v116, v116
	v_add_f32_e32 v155, v155, v158
	v_add_f32_e32 v154, v154, v155
	ds_bpermute_b32 v155, v172, v154
	s_waitcnt lgkmcnt(0)
	v_add_f32_e32 v154, v154, v155
	v_mov_b32_e32 v155, v154
	s_nop 1
	v_permlane32_swap_b32_e32 v154, v155
	s_and_saveexec_b64 s[54:55], s[42:43]
	v_add_f32_e32 v154, v154, v155
	ds_write_b32 v201, v154 offset:512
	s_or_b64 exec, exec, s[54:55]
	v_mul_f32_e32 v154, v127, v127
	v_mul_f32_e32 v155, v129, v129
	v_fmac_f32_e32 v154, v126, v126
	v_fmac_f32_e32 v155, v128, v128
	v_add_f32_e32 v154, v154, v155
	v_mul_f32_e32 v155, v123, v123
	v_mul_f32_e32 v158, v125, v125
	v_fmac_f32_e32 v155, v122, v122
	v_fmac_f32_e32 v158, v124, v124
	v_add_f32_e32 v155, v155, v158
	v_add_f32_e32 v154, v154, v155
	v_mul_f32_e32 v155, v111, v111
	v_mul_f32_e32 v158, v113, v113
	v_fmac_f32_e32 v155, v110, v110
	v_fmac_f32_e32 v158, v112, v112
	v_add_f32_e32 v155, v155, v158
	v_add_f32_e32 v154, v154, v155
	v_mul_f32_e32 v155, v107, v107
	v_mul_f32_e32 v158, v109, v109
	v_fmac_f32_e32 v155, v106, v106
	v_fmac_f32_e32 v158, v108, v108
	v_add_f32_e32 v155, v155, v158
	v_add_f32_e32 v154, v154, v155
	ds_bpermute_b32 v155, v172, v154
	s_waitcnt lgkmcnt(0)
	v_add_f32_e32 v154, v154, v155
	v_mov_b32_e32 v155, v154
	s_nop 1
	v_permlane32_swap_b32_e32 v154, v155
	s_and_saveexec_b64 s[54:55], s[42:43]
	v_add_f32_e32 v154, v154, v155
	ds_write_b32 v201, v154 offset:768
	s_or_b64 exec, exec, s[54:55]
	v_mul_f32_e32 v154, v87, v87
	v_mul_f32_e32 v155, v89, v89
	v_fmac_f32_e32 v154, v86, v86
	v_fmac_f32_e32 v155, v88, v88
	v_add_f32_e32 v154, v154, v155
	v_mul_f32_e32 v155, v83, v83
	v_mul_f32_e32 v158, v85, v85
	v_fmac_f32_e32 v155, v82, v82
	v_fmac_f32_e32 v158, v84, v84
	v_add_f32_e32 v155, v155, v158
	v_add_f32_e32 v154, v154, v155
	v_mul_f32_e32 v155, v71, v71
	v_mul_f32_e32 v158, v73, v73
	v_fmac_f32_e32 v155, v70, v70
	v_fmac_f32_e32 v158, v72, v72
	v_add_f32_e32 v155, v155, v158
	v_add_f32_e32 v154, v154, v155
	v_mul_f32_e32 v155, v67, v67
	v_mul_f32_e32 v158, v69, v69
	v_fmac_f32_e32 v155, v66, v66
	v_fmac_f32_e32 v158, v68, v68
	v_add_f32_e32 v155, v155, v158
	v_add_f32_e32 v154, v154, v155
	ds_bpermute_b32 v155, v172, v154
	s_waitcnt lgkmcnt(0)
; __device__ __forceinline__ float swap_add(float v) { auto rr = __builtin_amdgcn_permlane32_swap(__float_as_uint(v), __float_as_uint(v), false, false); return __uint_as_float(rr[0]) + __uint_as_float(rr[1]); }
;     __device__ __forceinline__ void exchange(const f32x4 (&acc)[2][2][4][2], const Unit& u, int e, int wr, int wc, int fr, int fq) const {
;     ...
;         for (int ai = 0; ai < 2; ++ai)
; #pragma unroll
;             for (int m = 0; m < 4; ++m) { float q = 0.f;
; #pragma unroll
;                 for (int bj = 0; bj < 2; ++bj)
; #pragma unroll
;                     for (int n = 0; n < 2; ++n) { const f32x4 v = acc[ai][bj][m][n]; q += (v[0] * v[0] + v[1] * v[1]) + (v[2] * v[2] + v[3] * v[3]); }
;                 q += __int_as_float(__builtin_amdgcn_ds_bpermute((lid ^ 16) << 2, __float_as_int(q))); q = swap_add(q);
;                 if (fq == 0) P[(ai * 128 + wr * 64 + m * 16 + fr) * 4 + wc] = q; }
;         __syncthreads();
;         float* xb = xbuf + (size_t)e * T * 4 + (size_t)u.pm * 256 * 4; unsigned* c = cnt + (e * 64 + u.pm) * 64;
;         if (tid < 256) { const float tot = (P[tid * 4] + P[tid * 4 + 1]) + (P[tid * 4 + 2] + P[tid * 4 + 3]);
;             __hip_atomic_store(xb + tid * 4 + u.pn, tot, __ATOMIC_RELAXED, __HIP_MEMORY_SCOPE_AGENT); }
	v_add_f32_e32 v154, v154, v155
	v_mov_b32_e32 v155, v154
	s_nop 1
	v_permlane32_swap_b32_e32 v154, v155
	s_and_saveexec_b64 s[54:55], s[42:43]
	v_add_f32_e32 v154, v154, v155
	ds_write_b32 v201, v154 offset:2048
	s_or_b64 exec, exec, s[54:55]
	v_mul_f32_e32 v154, v47, v47
	v_mul_f32_e32 v155, v49, v49
	v_fmac_f32_e32 v154, v46, v46
	v_fmac_f32_e32 v155, v48, v48
	v_add_f32_e32 v154, v154, v155
	v_mul_f32_e32 v155, v43, v43
	v_mul_f32_e32 v158, v45, v45
	v_fmac_f32_e32 v155, v42, v42
	v_fmac_f32_e32 v158, v44, v44
	v_add_f32_e32 v155, v155, v158
	v_add_f32_e32 v154, v154, v155
	v_mul_f32_e32 v155, v39, v39
	v_mul_f32_e32 v158, v41, v41
	v_fmac_f32_e32 v155, v38, v38
	v_fmac_f32_e32 v158, v40, v40
	v_add_f32_e32 v155, v155, v158
	v_add_f32_e32 v154, v154, v155
	v_mul_f32_e32 v155, v35, v35
	v_mul_f32_e32 v158, v37, v37
	v_fmac_f32_e32 v155, v34, v34
	v_fmac_f32_e32 v158, v36, v36
	v_add_f32_e32 v155, v155, v158
	v_add_f32_e32 v154, v154, v155
	ds_bpermute_b32 v155, v172, v154
	s_waitcnt lgkmcnt(0)
	v_add_f32_e32 v154, v154, v155
	v_mov_b32_e32 v155, v154
	s_nop 1
	v_permlane32_swap_b32_e32 v154, v155
	s_and_saveexec_b64 s[54:55], s[42:43]
	v_add_f32_e32 v154, v154, v155
	ds_write_b32 v201, v154 offset:2304
	s_or_b64 exec, exec, s[54:55]
	v_mul_f32_e32 v154, v31, v31
	v_mul_f32_e32 v155, v33, v33
	v_fmac_f32_e32 v154, v30, v30
	v_fmac_f32_e32 v155, v32, v32
	v_add_f32_e32 v154, v154, v155
	v_mul_f32_e32 v155, v27, v27
	v_mul_f32_e32 v158, v29, v29
	v_fmac_f32_e32 v155, v26, v26
	v_fmac_f32_e32 v158, v28, v28
	v_add_f32_e32 v155, v155, v158
	v_add_f32_e32 v154, v154, v155
	v_mul_f32_e32 v155, v23, v23
	v_mul_f32_e32 v158, v25, v25
	v_fmac_f32_e32 v155, v22, v22
	v_fmac_f32_e32 v158, v24, v24
	v_add_f32_e32 v155, v155, v158
	v_add_f32_e32 v154, v154, v155
	v_mul_f32_e32 v155, v19, v19
	v_mul_f32_e32 v158, v21, v21
	v_fmac_f32_e32 v155, v18, v18
	v_fmac_f32_e32 v158, v20, v20
	v_add_f32_e32 v155, v155, v158
	v_add_f32_e32 v154, v154, v155
	ds_bpermute_b32 v155, v172, v154
	s_waitcnt lgkmcnt(0)
	v_add_f32_e32 v154, v154, v155
	v_mov_b32_e32 v155, v154
	s_nop 1
	v_permlane32_swap_b32_e32 v154, v155
	s_and_saveexec_b64 s[54:55], s[42:43]
	v_add_f32_e32 v154, v154, v155
	ds_write_b32 v201, v154 offset:2560
	s_or_b64 exec, exec, s[54:55]
	v_mul_f32_e32 v154, v15, v15
	v_mul_f32_e32 v155, v17, v17
	v_fmac_f32_e32 v154, v14, v14
	v_fmac_f32_e32 v155, v16, v16
	v_add_f32_e32 v154, v154, v155
	v_mul_f32_e32 v155, v11, v11
	v_mul_f32_e32 v158, v13, v13
	v_fmac_f32_e32 v155, v10, v10
	v_fmac_f32_e32 v158, v12, v12
	v_add_f32_e32 v155, v155, v158
	v_add_f32_e32 v154, v154, v155
	v_mul_f32_e32 v155, v7, v7
	v_mul_f32_e32 v158, v9, v9
	v_fmac_f32_e32 v155, v6, v6
	v_fmac_f32_e32 v158, v8, v8
	v_add_f32_e32 v155, v155, v158
	v_add_f32_e32 v154, v154, v155
	v_mul_f32_e32 v155, v3, v3
	v_mul_f32_e32 v158, v5, v5
	v_fmac_f32_e32 v155, v2, v2
	v_fmac_f32_e32 v158, v4, v4
	v_add_f32_e32 v155, v155, v158
	v_add_f32_e32 v154, v154, v155
	ds_bpermute_b32 v155, v172, v154
	s_waitcnt lgkmcnt(0)
	v_add_f32_e32 v154, v154, v155
	v_mov_b32_e32 v155, v154
	s_nop 1
	v_permlane32_swap_b32_e32 v154, v155
	s_and_saveexec_b64 s[54:55], s[42:43]
	v_add_f32_e32 v154, v154, v155
	ds_write_b32 v201, v154 offset:2816
	s_or_b64 exec, exec, s[54:55]
	s_add_u32 s12, s92, s12
	s_addc_u32 s13, s94, s13
	v_lshl_add_u64 v[154:155], v[136:137], 0, s[12:13]
	s_waitcnt lgkmcnt(0)
	s_barrier
	s_and_saveexec_b64 s[12:13], s[44:45]
	s_cbranch_execz .LBB0_122
	ds_read_b128 v[202:205], v180
	s_ashr_i32 s79, s78, 31
	v_lshl_add_u64 v[160:161], s[78:79], 4, 0
	v_lshl_add_u64 v[160:161], v[160:161], 4, 0
	v_lshl_add_u64 v[160:161], v[160:161], 2, v[154:155]
	s_waitcnt lgkmcnt(0)
	v_mov_b32_e32 v158, v203
	v_mov_b32_e32 v159, v204
	v_mov_b32_e32 v203, v205
	v_pk_add_f32 v[158:159], v[158:159], v[202:203]
	s_nop 0
	v_pk_add_f32 v[158:159], v[158:159], v[158:159] op_sel:[0,1] op_sel_hi:[1,0]
	global_store_dword v[160:161], v158, off sc1

;     __device__ __forceinline__ void exchange(const f32x4 (&acc)[2][2][4][2], const Unit& u, int e, int wr, int wc, int fr, int fq) const {
;     ...
;         if (tid < 256) { float t4 = 0.f;
; #pragma unroll
;             for (int k = 0; k < 4; ++k) t4 += __hip_atomic_load(xb + tid * 4 + k, __ATOMIC_RELAXED, __HIP_MEMORY_SCOPE_AGENT);
;             S[tid] = 1.0f / sqrtf(t4 * (1.f / DM) + EPS); }
.LBB0_137:
	s_waitcnt vmcnt(0) lgkmcnt(0)
	s_waitcnt lgkmcnt(0)
	s_barrier
	s_and_saveexec_b64 s[12:13], s[44:45]
	s_cbranch_execz .LBB0_139
	global_load_dword v158, v[154:155], off sc1
	global_load_dword v159, v[154:155], off offset:1024 sc1
	global_load_dword v160, v[154:155], off offset:2048 sc1
	s_nop 0
	global_load_dword v154, v[154:155], off offset:3072 sc1
	s_mov_b32 s50, 0xf800000
	s_waitcnt vmcnt(3)
	v_add_f32_e32 v155, 0, v158
	s_waitcnt vmcnt(2)
	v_add_f32_e32 v155, v155, v159
	s_waitcnt vmcnt(1)
	v_add_f32_e32 v155, v155, v160
	s_waitcnt vmcnt(0)
	v_add_f32_e32 v154, v155, v154
	v_fmamk_f32 v154, v154, 0x3a800000, v193
	v_mul_f32_e32 v155, 0x4f800000, v154
	v_cmp_gt_f32_e32 vcc, s50, v154
	s_nop 1
	v_cndmask_b32_e32 v154, v154, v155, vcc
	v_sqrt_f32_e32 v155, v154
	s_nop 0
	v_add_u32_e32 v158, -1, v155
	v_add_u32_e32 v159, 1, v155
	v_fma_f32 v160, -v158, v155, v154
	v_fma_f32 v161, -v159, v155, v154
	v_cmp_ge_f32_e64 s[50:51], 0, v160
	s_nop 1
	v_cndmask_b32_e64 v155, v155, v158, s[50:51]
	v_cmp_lt_f32_e64 s[50:51], 0, v161
	s_nop 1
	v_cndmask_b32_e64 v155, v155, v159, s[50:51]
	v_mul_f32_e32 v158, 0x37800000, v155
	v_cndmask_b32_e32 v155, v155, v158, vcc
	v_cmp_class_f32_e32 vcc, v154, v194
	s_nop 1
	v_cndmask_b32_e32 v154, v155, v154, vcc
	v_div_scale_f32 v155, s[50:51], v154, v154, 1.0
	v_rcp_f32_e32 v158, v155
	v_div_scale_f32 v159, vcc, 1.0, v154, 1.0
	v_fma_f32 v160, -v155, v158, 1.0
	v_fmac_f32_e32 v158, v160, v158
	v_mul_f32_e32 v160, v159, v158
	v_fma_f32 v161, -v155, v160, v159
	v_fmac_f32_e32 v160, v161, v158
	v_fma_f32 v155, -v155, v160, v159
	v_div_fmas_f32 v155, v155, v158, v160
	v_div_fixup_f32 v154, v155, v154, 1.0
	ds_write_b32 v181, v154

; __device__ __forceinline__ float swap_add(float v) { auto rr = __builtin_amdgcn_permlane32_swap(__float_as_uint(v), __float_as_uint(v), false, false); return __uint_as_float(rr[0]) + __uint_as_float(rr[1]); }
;     __device__ __forceinline__ void exchange(const f32x4 (&acc)[2][2][4][2], const Unit& u, int e, int wr, int wc, int fr, int fq) const {
;     ...
;         for (int ai = 0; ai < 2; ++ai)
; #pragma unroll
;             for (int m = 0; m < 4; ++m) { float q = 0.f;
; #pragma unroll
;                 for (int bj = 0; bj < 2; ++bj)
; #pragma unroll
;                     for (int n = 0; n < 2; ++n) { const f32x4 v = acc[ai][bj][m][n]; q += (v[0] * v[0] + v[1] * v[1]) + (v[2] * v[2] + v[3] * v[3]); }
;                 q += __int_as_float(__builtin_amdgcn_ds_bpermute((lid ^ 16) << 2, __float_as_int(q))); q = swap_add(q);
;                 if (fq == 0) P[(ai * 128 + wr * 64 + m * 16 + fr) * 4 + wc] = q; }
.LBB0_200:
	v_mul_f32_e32 v142, v43, v43
	v_mul_f32_e32 v143, v45, v45
	v_fmac_f32_e32 v142, v42, v42
	v_fmac_f32_e32 v143, v44, v44
	v_add_f32_e32 v142, v142, v143
	v_mul_f32_e32 v143, v47, v47
	v_mul_f32_e32 v144, v49, v49
	v_fmac_f32_e32 v143, v46, v46
	v_fmac_f32_e32 v144, v48, v48
	v_add_f32_e32 v143, v143, v144
	v_add_f32_e32 v142, v142, v143
	v_mul_f32_e32 v143, v63, v63
	v_mul_f32_e32 v144, v65, v65
	v_fmac_f32_e32 v143, v62, v62
	v_fmac_f32_e32 v144, v64, v64
	v_add_f32_e32 v143, v143, v144
	v_add_f32_e32 v142, v142, v143
	v_mul_f32_e32 v143, v59, v59
	v_mul_f32_e32 v144, v61, v61
	v_fmac_f32_e32 v143, v58, v58
	v_fmac_f32_e32 v144, v60, v60
	v_add_f32_e32 v143, v143, v144
	v_add_f32_e32 v142, v142, v143
	ds_bpermute_b32 v143, v171, v142
	s_waitcnt lgkmcnt(0)
	v_add_f32_e32 v142, v142, v143
	v_mov_b32_e32 v143, v142
	s_nop 1
	v_permlane32_swap_b32_e32 v142, v143
	s_and_saveexec_b64 s[12:13], s[42:43]
	v_add_f32_e32 v142, v142, v143
	ds_write_b32 v191, v142
	s_or_b64 exec, exec, s[12:13]
	v_mul_f32_e32 v142, v67, v67
	v_mul_f32_e32 v143, v69, v69
	v_fmac_f32_e32 v142, v66, v66
	v_fmac_f32_e32 v143, v68, v68
	v_add_f32_e32 v142, v142, v143
	v_mul_f32_e32 v143, v71, v71
	v_mul_f32_e32 v144, v73, v73
	v_fmac_f32_e32 v143, v70, v70
	v_fmac_f32_e32 v144, v72, v72
	v_add_f32_e32 v143, v143, v144
	v_add_f32_e32 v142, v142, v143
	v_mul_f32_e32 v143, v87, v87
	v_mul_f32_e32 v144, v89, v89
	v_fmac_f32_e32 v143, v86, v86
	v_fmac_f32_e32 v144, v88, v88
	v_add_f32_e32 v143, v143, v144
	v_add_f32_e32 v142, v142, v143
	v_mul_f32_e32 v143, v83, v83
	v_mul_f32_e32 v144, v85, v85
	v_fmac_f32_e32 v143, v82, v82
	v_fmac_f32_e32 v144, v84, v84
	v_add_f32_e32 v143, v143, v144
	v_add_f32_e32 v142, v142, v143
	ds_bpermute_b32 v143, v171, v142
	s_waitcnt lgkmcnt(0)
	v_add_f32_e32 v142, v142, v143
	v_mov_b32_e32 v143, v142
	s_nop 1
	v_permlane32_swap_b32_e32 v142, v143
	s_and_saveexec_b64 s[12:13], s[42:43]
	v_add_f32_e32 v142, v142, v143
	ds_write_b32 v191, v142 offset:256
	s_or_b64 exec, exec, s[12:13]
	v_mul_f32_e32 v142, v99, v99
	v_mul_f32_e32 v143, v101, v101
	v_fmac_f32_e32 v142, v98, v98
	v_fmac_f32_e32 v143, v100, v100
	v_add_f32_e32 v142, v142, v143
	v_mul_f32_e32 v143, v103, v103
	v_mul_f32_e32 v144, v105, v105
	v_fmac_f32_e32 v143, v102, v102
	v_fmac_f32_e32 v144, v104, v104
	v_add_f32_e32 v143, v143, v144
	v_add_f32_e32 v142, v142, v143
	v_mul_f32_e32 v143, v111, v111
	v_mul_f32_e32 v144, v113, v113
	v_fmac_f32_e32 v143, v110, v110
	v_fmac_f32_e32 v144, v112, v112
	v_add_f32_e32 v143, v143, v144
	v_add_f32_e32 v142, v142, v143
	v_mul_f32_e32 v143, v107, v107
	v_mul_f32_e32 v144, v109, v109
	v_fmac_f32_e32 v143, v106, v106
	v_fmac_f32_e32 v144, v108, v108
	v_add_f32_e32 v143, v143, v144
	v_add_f32_e32 v142, v142, v143
	ds_bpermute_b32 v143, v171, v142
	s_waitcnt lgkmcnt(0)
	v_add_f32_e32 v142, v142, v143
	v_mov_b32_e32 v143, v142
	s_nop 1
	v_permlane32_swap_b32_e32 v142, v143
	s_and_saveexec_b64 s[12:13], s[42:43]
	v_add_f32_e32 v142, v142, v143
	ds_write_b32 v191, v142 offset:512
	s_or_b64 exec, exec, s[12:13]
	v_mul_f32_e32 v142, v123, v123
	v_mul_f32_e32 v143, v125, v125
	v_fmac_f32_e32 v142, v122, v122
	v_fmac_f32_e32 v143, v124, v124
	v_add_f32_e32 v142, v142, v143
	v_mul_f32_e32 v143, v127, v127
	v_mul_f32_e32 v144, v129, v129
	v_fmac_f32_e32 v143, v126, v126
	v_fmac_f32_e32 v144, v128, v128
	v_add_f32_e32 v143, v143, v144
	v_add_f32_e32 v142, v142, v143
	v_mul_f32_e32 v143, v119, v119
	v_mul_f32_e32 v144, v121, v121
	v_fmac_f32_e32 v143, v118, v118
	v_fmac_f32_e32 v144, v120, v120
	v_add_f32_e32 v143, v143, v144
	v_add_f32_e32 v142, v142, v143
	v_mul_f32_e32 v143, v115, v115
	v_mul_f32_e32 v144, v117, v117
	v_fmac_f32_e32 v143, v114, v114
	v_fmac_f32_e32 v144, v116, v116
	v_add_f32_e32 v143, v143, v144
	v_add_f32_e32 v142, v142, v143
	ds_bpermute_b32 v143, v171, v142
	s_waitcnt lgkmcnt(0)
	v_add_f32_e32 v142, v142, v143
	v_mov_b32_e32 v143, v142
	s_nop 1
	v_permlane32_swap_b32_e32 v142, v143
	s_and_saveexec_b64 s[12:13], s[42:43]
	v_add_f32_e32 v142, v142, v143
	ds_write_b32 v191, v142 offset:768
	s_or_b64 exec, exec, s[12:13]
	v_mul_f32_e32 v142, v95, v95
	v_mul_f32_e32 v143, v97, v97
	v_fmac_f32_e32 v142, v94, v94
	v_fmac_f32_e32 v143, v96, v96
	v_add_f32_e32 v142, v142, v143
	v_mul_f32_e32 v143, v91, v91
	v_mul_f32_e32 v144, v93, v93
	v_fmac_f32_e32 v143, v90, v90
	v_fmac_f32_e32 v144, v92, v92
	v_add_f32_e32 v143, v143, v144
	v_add_f32_e32 v142, v142, v143
	v_mul_f32_e32 v143, v79, v79
	v_mul_f32_e32 v144, v81, v81
	v_fmac_f32_e32 v143, v78, v78
	v_fmac_f32_e32 v144, v80, v80
	v_add_f32_e32 v143, v143, v144
	v_add_f32_e32 v142, v142, v143
	v_mul_f32_e32 v143, v75, v75
	v_mul_f32_e32 v144, v77, v77
	v_fmac_f32_e32 v143, v74, v74
	v_fmac_f32_e32 v144, v76, v76
	v_add_f32_e32 v143, v143, v144
	v_add_f32_e32 v142, v142, v143
	ds_bpermute_b32 v143, v171, v142
	s_waitcnt lgkmcnt(0)
; __device__ __forceinline__ float swap_add(float v) { auto rr = __builtin_amdgcn_permlane32_swap(__float_as_uint(v), __float_as_uint(v), false, false); return __uint_as_float(rr[0]) + __uint_as_float(rr[1]); }
;     __device__ __forceinline__ void exchange(const f32x4 (&acc)[2][2][4][2], const Unit& u, int e, int wr, int wc, int fr, int fq) const {
;     ...
;         for (int ai = 0; ai < 2; ++ai)
; #pragma unroll
;             for (int m = 0; m < 4; ++m) { float q = 0.f;
; #pragma unroll
;                 for (int bj = 0; bj < 2; ++bj)
; #pragma unroll
;                     for (int n = 0; n < 2; ++n) { const f32x4 v = acc[ai][bj][m][n]; q += (v[0] * v[0] + v[1] * v[1]) + (v[2] * v[2] + v[3] * v[3]); }
;                 q += __int_as_float(__builtin_amdgcn_ds_bpermute((lid ^ 16) << 2, __float_as_int(q))); q = swap_add(q);
;                 if (fq == 0) P[(ai * 128 + wr * 64 + m * 16 + fr) * 4 + wc] = q; }
;         __syncthreads();
;         float* xb = xbuf + (size_t)e * T * 4 + (size_t)u.pm * 256 * 4; unsigned* c = cnt + (e * 64 + u.pm) * 64;
;         if (tid < 256) { const float tot = (P[tid * 4] + P[tid * 4 + 1]) + (P[tid * 4 + 2] + P[tid * 4 + 3]);
;             __hip_atomic_store(xb + tid * 4 + u.pn, tot, __ATOMIC_RELAXED, __HIP_MEMORY_SCOPE_AGENT); }
	v_add_f32_e32 v142, v142, v143
	v_mov_b32_e32 v143, v142
	s_nop 1
	v_permlane32_swap_b32_e32 v142, v143
	s_and_saveexec_b64 s[12:13], s[42:43]
	v_add_f32_e32 v142, v142, v143
	ds_write_b32 v191, v142 offset:2048
	s_or_b64 exec, exec, s[12:13]
	v_mul_f32_e32 v142, v55, v55
	v_mul_f32_e32 v143, v57, v57
	v_fmac_f32_e32 v142, v54, v54
	v_fmac_f32_e32 v143, v56, v56
	v_add_f32_e32 v142, v142, v143
	v_mul_f32_e32 v143, v51, v51
	v_mul_f32_e32 v144, v53, v53
	v_fmac_f32_e32 v143, v50, v50
	v_fmac_f32_e32 v144, v52, v52
	v_add_f32_e32 v143, v143, v144
	v_add_f32_e32 v142, v142, v143
	v_mul_f32_e32 v143, v39, v39
	v_mul_f32_e32 v144, v41, v41
	v_fmac_f32_e32 v143, v38, v38
	v_fmac_f32_e32 v144, v40, v40
	v_add_f32_e32 v143, v143, v144
	v_add_f32_e32 v142, v142, v143
	v_mul_f32_e32 v143, v35, v35
	v_mul_f32_e32 v144, v37, v37
	v_fmac_f32_e32 v143, v34, v34
	v_fmac_f32_e32 v144, v36, v36
	v_add_f32_e32 v143, v143, v144
	v_add_f32_e32 v142, v142, v143
	ds_bpermute_b32 v143, v171, v142
	s_waitcnt lgkmcnt(0)
	v_add_f32_e32 v142, v142, v143
	v_mov_b32_e32 v143, v142
	s_nop 1
	v_permlane32_swap_b32_e32 v142, v143
	s_and_saveexec_b64 s[12:13], s[42:43]
	v_add_f32_e32 v142, v142, v143
	ds_write_b32 v191, v142 offset:2304
	s_or_b64 exec, exec, s[12:13]
	v_mul_f32_e32 v142, v31, v31
	v_mul_f32_e32 v143, v33, v33
	v_fmac_f32_e32 v142, v30, v30
	v_fmac_f32_e32 v143, v32, v32
	v_add_f32_e32 v142, v142, v143
	v_mul_f32_e32 v143, v27, v27
	v_mul_f32_e32 v144, v29, v29
	v_fmac_f32_e32 v143, v26, v26
	v_fmac_f32_e32 v144, v28, v28
	v_add_f32_e32 v143, v143, v144
	v_add_f32_e32 v142, v142, v143
	v_mul_f32_e32 v143, v23, v23
	v_mul_f32_e32 v144, v25, v25
	v_fmac_f32_e32 v143, v22, v22
	v_fmac_f32_e32 v144, v24, v24
	v_add_f32_e32 v143, v143, v144
	v_add_f32_e32 v142, v142, v143
	v_mul_f32_e32 v143, v19, v19
	v_mul_f32_e32 v144, v21, v21
	v_fmac_f32_e32 v143, v18, v18
	v_fmac_f32_e32 v144, v20, v20
	v_add_f32_e32 v143, v143, v144
	v_add_f32_e32 v142, v142, v143
	ds_bpermute_b32 v143, v171, v142
	s_waitcnt lgkmcnt(0)
	v_add_f32_e32 v142, v142, v143
	v_mov_b32_e32 v143, v142
	s_nop 1
	v_permlane32_swap_b32_e32 v142, v143
	s_and_saveexec_b64 s[12:13], s[42:43]
	v_add_f32_e32 v142, v142, v143
	ds_write_b32 v191, v142 offset:2560
	s_or_b64 exec, exec, s[12:13]
	v_mul_f32_e32 v142, v15, v15
	v_mul_f32_e32 v143, v17, v17
	v_fmac_f32_e32 v142, v14, v14
	v_fmac_f32_e32 v143, v16, v16
	v_add_f32_e32 v142, v142, v143
	v_mul_f32_e32 v143, v11, v11
	v_mul_f32_e32 v144, v13, v13
	v_fmac_f32_e32 v143, v10, v10
	v_fmac_f32_e32 v144, v12, v12
	v_add_f32_e32 v143, v143, v144
	v_add_f32_e32 v142, v142, v143
	v_mul_f32_e32 v143, v7, v7
	v_mul_f32_e32 v144, v9, v9
	v_fmac_f32_e32 v143, v6, v6
	v_fmac_f32_e32 v144, v8, v8
	v_add_f32_e32 v143, v143, v144
	v_add_f32_e32 v142, v142, v143
	v_mul_f32_e32 v143, v3, v3
	v_mul_f32_e32 v144, v5, v5
	v_fmac_f32_e32 v143, v2, v2
	v_fmac_f32_e32 v144, v4, v4
	v_add_f32_e32 v143, v143, v144
	v_add_f32_e32 v142, v142, v143
	ds_bpermute_b32 v143, v171, v142
	s_waitcnt lgkmcnt(0)
	v_add_f32_e32 v142, v142, v143
	v_mov_b32_e32 v143, v142
	s_nop 1
	v_permlane32_swap_b32_e32 v142, v143
	s_and_saveexec_b64 s[12:13], s[42:43]
	v_add_f32_e32 v142, v142, v143
	ds_write_b32 v191, v142 offset:2816
	s_or_b64 exec, exec, s[12:13]
	s_ashr_i32 s83, s82, 31
	s_lshl_b64 s[12:13], s[82:83], 12
	s_add_u32 s50, s36, s12
	s_addc_u32 s51, s18, s13
	v_lshl_add_u64 v[142:143], v[136:137], 0, s[50:51]
	s_waitcnt vmcnt(0) lgkmcnt(0)
	s_barrier
	s_and_saveexec_b64 s[50:51], s[44:45]
	s_cbranch_execz .LBB0_218
	ds_read_b128 v[144:147], v179
	s_ashr_i32 s77, s76, 31
	s_waitcnt lgkmcnt(0)
	v_mov_b32_e32 v148, v145
	v_mov_b32_e32 v149, v146
	v_mov_b32_e32 v145, v147
	v_pk_add_f32 v[144:145], v[148:149], v[144:145]
	v_lshl_add_u64 v[146:147], s[76:77], 4, 0
	v_lshl_add_u64 v[146:147], v[146:147], 4, 0
	v_lshl_add_u64 v[146:147], v[146:147], 2, v[142:143]
	v_pk_add_f32 v[144:145], v[144:145], v[144:145] op_sel:[0,1] op_sel_hi:[1,0]
	global_store_dword v[146:147], v144, off sc1

; #define LAS __attribute__((address_space(3)))
;     __device__ __forceinline__ void exchange(const f32x4 (&acc)[2][2][4][2], const Unit& u, int e, int wr, int wc, int fr, int fq) const {
;     ...
;         if (tid < 256) { float t4 = 0.f;
; #pragma unroll
;             for (int k = 0; k < 4; ++k) t4 += __hip_atomic_load(xb + tid * 4 + k, __ATOMIC_RELAXED, __HIP_MEMORY_SCOPE_AGENT);
;             S[tid] = 1.0f / sqrtf(t4 * (1.f / DM) + EPS); }
;         __syncthreads();
;     }
;     __device__ __forceinline__ void operator()(f32x4 (&acc)[2][2][4][2], const Unit& u, int wr, int wc, int fr, int fq) const {
;         const LAS float* S = (const LAS float*)(lds + EN_S);
;         const int col0 = u.pn * 256 + wc * 32 + 8 * fq;
;         exchange(acc, u, 0, wr, wc, fr, fq);
; #pragma unroll
;         for (int ai = 0; ai < 2; ++ai)
; #pragma unroll
;             for (int m = 0; m < 4; ++m) { const int rl = ai * 128 + wr * 64 + m * 16 + fr; const float r1 = S[rl]; const size_t off = (size_t)(u.pm * 256 + rl) * DM + col0;
; #pragma unroll
;                 for (int bj = 0; bj < 2; ++bj) { const f32x4 xa = *(const f32x4*)(xin + off + bj * 128), xb = *(const f32x4*)(xin + off + bj * 128 + 4);
;                     const f32x4 ga = *(const f32x4*)(gpost + col0 + bj * 128), gb = *(const f32x4*)(gpost + col0 + bj * 128 + 4);
;                     const f32x4 v0 = xa + acc[ai][bj][m][0] * r1 * ga, v1 = xb + acc[ai][bj][m][1] * r1 * gb;
;                     *(f32x4*)(xout + off + bj * 128) = v0; *(f32x4*)(xout + off + bj * 128 + 4) = v1; acc[ai][bj][m][0] = v0; acc[ai][bj][m][1] = v1; }
.LBB0_233:
	s_waitcnt vmcnt(0) lgkmcnt(0)
	s_waitcnt lgkmcnt(0)
	s_barrier
	s_and_saveexec_b64 s[84:85], s[44:45]
	s_cbranch_execz .LBB0_235
	global_load_dword v144, v[142:143], off sc1
	global_load_dword v145, v[142:143], off offset:1024 sc1
	global_load_dword v146, v[142:143], off offset:2048 sc1
	s_nop 0
	global_load_dword v142, v[142:143], off offset:3072 sc1
	s_mov_b32 s54, 0xf800000
	s_waitcnt vmcnt(3)
	v_add_f32_e32 v143, 0, v144
	s_waitcnt vmcnt(2)
	v_add_f32_e32 v143, v143, v145
	s_waitcnt vmcnt(1)
	v_add_f32_e32 v143, v143, v146
	s_waitcnt vmcnt(0)
	v_add_f32_e32 v142, v143, v142
	v_fmamk_f32 v142, v142, 0x3a800000, v193
	v_mul_f32_e32 v143, 0x4f800000, v142
	v_cmp_gt_f32_e32 vcc, s54, v142
	s_nop 1
	v_cndmask_b32_e32 v142, v142, v143, vcc
	v_sqrt_f32_e32 v143, v142
	s_nop 0
	v_add_u32_e32 v144, -1, v143
	v_add_u32_e32 v145, 1, v143
	v_fma_f32 v146, -v144, v143, v142
	v_fma_f32 v147, -v145, v143, v142
	v_cmp_ge_f32_e64 s[54:55], 0, v146
	s_nop 1
	v_cndmask_b32_e64 v143, v143, v144, s[54:55]
	v_cmp_lt_f32_e64 s[54:55], 0, v147
	s_nop 1
	v_cndmask_b32_e64 v143, v143, v145, s[54:55]
	v_mul_f32_e32 v144, 0x37800000, v143
	v_cndmask_b32_e32 v143, v143, v144, vcc
	v_cmp_class_f32_e32 vcc, v142, v194
	s_nop 1
	v_cndmask_b32_e32 v142, v143, v142, vcc
	v_div_scale_f32 v143, s[54:55], v142, v142, 1.0
	v_rcp_f32_e32 v144, v143
	v_div_scale_f32 v145, vcc, 1.0, v142, 1.0
	v_fma_f32 v146, -v143, v144, 1.0
	v_fmac_f32_e32 v144, v146, v144
	v_mul_f32_e32 v146, v145, v144
	v_fma_f32 v147, -v143, v146, v145
	v_fmac_f32_e32 v146, v147, v144
	v_fma_f32 v143, -v143, v146, v145
	v_div_fmas_f32 v143, v143, v144, v146
	v_div_fixup_f32 v142, v143, v142, 1.0
	ds_write_b32 v180, v142
.LBB0_235:
	s_or_b64 exec, exec, s[84:85]
	s_lshl_b32 s54, s82, 8
	v_add_u32_e32 v144, s54, v169
	v_lshl_or_b32 v142, s76, 8, v189
	v_ashrrev_i32_e32 v145, 31, v144
	v_ashrrev_i32_e32 v143, 31, v142
	v_lshlrev_b64 v[146:147], 10, v[144:145]
	v_lshl_add_u64 v[146:147], v[146:147], 0, v[142:143]
	v_lshlrev_b64 v[162:163], 2, v[146:147]
	v_lshl_add_u64 v[164:165], s[34:35], 0, v[162:163]
	v_lshl_add_u64 v[154:155], v[142:143], 2, s[52:53]
	global_load_dwordx4 v[218:221], v[154:155], off
	global_load_dwordx4 v[222:225], v[154:155], off offset:16
	global_load_dwordx4 v[226:229], v[154:155], off offset:512
	global_load_dwordx4 v[230:233], v[154:155], off offset:528
	s_waitcnt lgkmcnt(0)
	s_barrier
	s_andn2_b64 vcc, exec, s[70:71]
	ds_read_b32 v154, v181
	global_load_dwordx4 v[202:205], v[164:165], off offset:16
	global_load_dwordx4 v[206:209], v[164:165], off
	global_load_dwordx4 v[210:213], v[164:165], off offset:528
	global_load_dwordx4 v[214:217], v[164:165], off offset:512
	v_lshl_add_u64 v[162:163], s[14:15], 0, v[162:163]
	v_add_u32_e32 v250, s54, v172
	v_ashrrev_i32_e32 v251, 31, v250
	v_lshlrev_b64 v[250:251], 10, v[250:251]
	v_lshl_add_u64 v[250:251], v[250:251], 0, v[142:143]
	v_lshlrev_b64 v[250:251], 2, v[250:251]
	v_lshl_add_u64 v[158:159], s[34:35], 0, v[250:251]
	v_lshl_add_u64 v[160:161], s[14:15], 0, v[250:251]
	ds_read_b32 v156, v182
	global_load_dwordx4 v[234:237], v[158:159], off offset:16
	global_load_dwordx4 v[238:241], v[158:159], off
	global_load_dwordx4 v[146:149], v[158:159], off offset:528
	global_load_dwordx4 v[150:153], v[158:159], off offset:512
	s_waitcnt lgkmcnt(1)
	v_pk_mul_f32 v[42:43], v[42:43], v[154:155] op_sel_hi:[1,0]
	v_pk_mul_f32 v[44:45], v[44:45], v[154:155] op_sel_hi:[1,0]
	v_pk_mul_f32 v[46:47], v[46:47], v[154:155] op_sel_hi:[1,0]
	v_pk_mul_f32 v[48:49], v[48:49], v[154:155] op_sel_hi:[1,0]
	v_pk_mul_f32 v[62:63], v[62:63], v[154:155] op_sel_hi:[1,0]
	v_pk_mul_f32 v[64:65], v[64:65], v[154:155] op_sel_hi:[1,0]
	v_pk_mul_f32 v[58:59], v[58:59], v[154:155] op_sel_hi:[1,0]
	v_pk_mul_f32 v[60:61], v[60:61], v[154:155] op_sel_hi:[1,0]
	s_waitcnt vmcnt(4)
	v_pk_fma_f32 v[46:47], v[46:47], v[222:223], v[202:203]
	v_pk_fma_f32 v[48:49], v[48:49], v[224:225], v[204:205]
	v_pk_fma_f32 v[42:43], v[42:43], v[218:219], v[206:207]
	v_pk_fma_f32 v[44:45], v[44:45], v[220:221], v[208:209]
	v_pk_fma_f32 v[58:59], v[58:59], v[230:231], v[210:211]
	v_pk_fma_f32 v[60:61], v[60:61], v[232:233], v[212:213]
	v_pk_fma_f32 v[62:63], v[62:63], v[226:227], v[214:215]
	v_pk_fma_f32 v[64:65], v[64:65], v[228:229], v[216:217]
	global_store_dwordx4 v[162:163], v[42:45], off
	global_store_dwordx4 v[162:163], v[46:49], off offset:16
	global_store_dwordx4 v[162:163], v[62:65], off offset:512
	global_store_dwordx4 v[162:163], v[58:61], off offset:528
	v_add_u32_e32 v250, s54, v173
	v_ashrrev_i32_e32 v251, 31, v250
	v_lshlrev_b64 v[250:251], 10, v[250:251]
	v_lshl_add_u64 v[250:251], v[250:251], 0, v[142:143]
	v_lshlrev_b64 v[250:251], 2, v[250:251]
	v_lshl_add_u64 v[164:165], s[34:35], 0, v[250:251]
	v_lshl_add_u64 v[162:163], s[14:15], 0, v[250:251]
	ds_read_b32 v154, v183
	global_load_dwordx4 v[202:205], v[164:165], off offset:16
	global_load_dwordx4 v[206:209], v[164:165], off
	global_load_dwordx4 v[210:213], v[164:165], off offset:528
	global_load_dwordx4 v[214:217], v[164:165], off offset:512
	s_waitcnt lgkmcnt(1)
	v_pk_mul_f32 v[66:67], v[66:67], v[156:157] op_sel_hi:[1,0]
	v_pk_mul_f32 v[68:69], v[68:69], v[156:157] op_sel_hi:[1,0]
	v_pk_mul_f32 v[70:71], v[70:71], v[156:157] op_sel_hi:[1,0]
	v_pk_mul_f32 v[72:73], v[72:73], v[156:157] op_sel_hi:[1,0]
	v_pk_mul_f32 v[86:87], v[86:87], v[156:157] op_sel_hi:[1,0]
	v_pk_mul_f32 v[88:89], v[88:89], v[156:157] op_sel_hi:[1,0]
	v_pk_mul_f32 v[82:83], v[82:83], v[156:157] op_sel_hi:[1,0]
	v_pk_mul_f32 v[84:85], v[84:85], v[156:157] op_sel_hi:[1,0]
	s_waitcnt vmcnt(8)
;     __device__ __forceinline__ void operator()(f32x4 (&acc)[2][2][4][2], const Unit& u, int wr, int wc, int fr, int fq) const {
;     ...
; #pragma unroll
;         for (int ai = 0; ai < 2; ++ai)
; #pragma unroll
;             for (int m = 0; m < 4; ++m) { const int rl = ai * 128 + wr * 64 + m * 16 + fr; const float r1 = S[rl]; const size_t off = (size_t)(u.pm * 256 + rl) * DM + col0;
; #pragma unroll
;                 for (int bj = 0; bj < 2; ++bj) { const f32x4 xa = *(const f32x4*)(xin + off + bj * 128), xb = *(const f32x4*)(xin + off + bj * 128 + 4);
;                     const f32x4 ga = *(const f32x4*)(gpost + col0 + bj * 128), gb = *(const f32x4*)(gpost + col0 + bj * 128 + 4);
;                     const f32x4 v0 = xa + acc[ai][bj][m][0] * r1 * ga, v1 = xb + acc[ai][bj][m][1] * r1 * gb;
;                     *(f32x4*)(xout + off + bj * 128) = v0; *(f32x4*)(xout + off + bj * 128 + 4) = v1; acc[ai][bj][m][0] = v0; acc[ai][bj][m][1] = v1; }
;                 asm volatile("" ::: "memory"); }
	v_pk_fma_f32 v[70:71], v[70:71], v[222:223], v[234:235]
	v_pk_fma_f32 v[72:73], v[72:73], v[224:225], v[236:237]
	v_pk_fma_f32 v[66:67], v[66:67], v[218:219], v[238:239]
	v_pk_fma_f32 v[68:69], v[68:69], v[220:221], v[240:241]
	v_pk_fma_f32 v[82:83], v[82:83], v[230:231], v[146:147]
	v_pk_fma_f32 v[84:85], v[84:85], v[232:233], v[148:149]
	v_pk_fma_f32 v[86:87], v[86:87], v[226:227], v[150:151]
	v_pk_fma_f32 v[88:89], v[88:89], v[228:229], v[152:153]
	global_store_dwordx4 v[160:161], v[66:69], off
	global_store_dwordx4 v[160:161], v[70:73], off offset:16
	global_store_dwordx4 v[160:161], v[86:89], off offset:512
	global_store_dwordx4 v[160:161], v[82:85], off offset:528
	v_add_u32_e32 v250, s54, v174
	v_ashrrev_i32_e32 v251, 31, v250
	v_lshlrev_b64 v[250:251], 10, v[250:251]
	v_lshl_add_u64 v[250:251], v[250:251], 0, v[142:143]
	v_lshlrev_b64 v[250:251], 2, v[250:251]
	v_lshl_add_u64 v[158:159], s[34:35], 0, v[250:251]
	v_lshl_add_u64 v[160:161], s[14:15], 0, v[250:251]
	ds_read_b32 v156, v184
	global_load_dwordx4 v[234:237], v[158:159], off offset:16
	global_load_dwordx4 v[238:241], v[158:159], off
	global_load_dwordx4 v[146:149], v[158:159], off offset:528
	global_load_dwordx4 v[150:153], v[158:159], off offset:512
	s_waitcnt lgkmcnt(1)
	v_pk_mul_f32 v[98:99], v[98:99], v[154:155] op_sel_hi:[1,0]
	v_pk_mul_f32 v[100:101], v[100:101], v[154:155] op_sel_hi:[1,0]
	v_pk_mul_f32 v[102:103], v[102:103], v[154:155] op_sel_hi:[1,0]
	v_pk_mul_f32 v[104:105], v[104:105], v[154:155] op_sel_hi:[1,0]
	v_pk_mul_f32 v[110:111], v[110:111], v[154:155] op_sel_hi:[1,0]
	v_pk_mul_f32 v[112:113], v[112:113], v[154:155] op_sel_hi:[1,0]
	v_pk_mul_f32 v[106:107], v[106:107], v[154:155] op_sel_hi:[1,0]
	v_pk_mul_f32 v[108:109], v[108:109], v[154:155] op_sel_hi:[1,0]
	s_waitcnt vmcnt(8)
	v_pk_fma_f32 v[102:103], v[102:103], v[222:223], v[202:203]
	v_pk_fma_f32 v[104:105], v[104:105], v[224:225], v[204:205]
	v_pk_fma_f32 v[98:99], v[98:99], v[218:219], v[206:207]
	v_pk_fma_f32 v[100:101], v[100:101], v[220:221], v[208:209]
	v_pk_fma_f32 v[106:107], v[106:107], v[230:231], v[210:211]
	v_pk_fma_f32 v[108:109], v[108:109], v[232:233], v[212:213]
	v_pk_fma_f32 v[110:111], v[110:111], v[226:227], v[214:215]
	v_pk_fma_f32 v[112:113], v[112:113], v[228:229], v[216:217]
	global_store_dwordx4 v[162:163], v[98:101], off
	global_store_dwordx4 v[162:163], v[102:105], off offset:16
	global_store_dwordx4 v[162:163], v[110:113], off offset:512
	global_store_dwordx4 v[162:163], v[106:109], off offset:528
	v_add_u32_e32 v250, s54, v175
	v_ashrrev_i32_e32 v251, 31, v250
	v_lshlrev_b64 v[250:251], 10, v[250:251]
	v_lshl_add_u64 v[250:251], v[250:251], 0, v[142:143]
	v_lshlrev_b64 v[250:251], 2, v[250:251]
	v_lshl_add_u64 v[164:165], s[34:35], 0, v[250:251]
	v_lshl_add_u64 v[162:163], s[14:15], 0, v[250:251]
	ds_read_b32 v154, v185
	global_load_dwordx4 v[202:205], v[164:165], off offset:16
	global_load_dwordx4 v[206:209], v[164:165], off
	global_load_dwordx4 v[210:213], v[164:165], off offset:528
	global_load_dwordx4 v[214:217], v[164:165], off offset:512
	s_waitcnt lgkmcnt(1)
	v_pk_mul_f32 v[122:123], v[122:123], v[156:157] op_sel_hi:[1,0]
	v_pk_mul_f32 v[124:125], v[124:125], v[156:157] op_sel_hi:[1,0]
	v_pk_mul_f32 v[126:127], v[126:127], v[156:157] op_sel_hi:[1,0]
	v_pk_mul_f32 v[128:129], v[128:129], v[156:157] op_sel_hi:[1,0]
	v_pk_mul_f32 v[118:119], v[118:119], v[156:157] op_sel_hi:[1,0]
	v_pk_mul_f32 v[120:121], v[120:121], v[156:157] op_sel_hi:[1,0]
	v_pk_mul_f32 v[114:115], v[114:115], v[156:157] op_sel_hi:[1,0]
	v_pk_mul_f32 v[116:117], v[116:117], v[156:157] op_sel_hi:[1,0]
	s_waitcnt vmcnt(8)
	v_pk_fma_f32 v[126:127], v[126:127], v[222:223], v[234:235]
	v_pk_fma_f32 v[128:129], v[128:129], v[224:225], v[236:237]
	v_pk_fma_f32 v[122:123], v[122:123], v[218:219], v[238:239]
	v_pk_fma_f32 v[124:125], v[124:125], v[220:221], v[240:241]
	v_pk_fma_f32 v[114:115], v[114:115], v[230:231], v[146:147]
	v_pk_fma_f32 v[116:117], v[116:117], v[232:233], v[148:149]
	v_pk_fma_f32 v[118:119], v[118:119], v[226:227], v[150:151]
	v_pk_fma_f32 v[120:121], v[120:121], v[228:229], v[152:153]
	global_store_dwordx4 v[160:161], v[122:125], off
	global_store_dwordx4 v[160:161], v[126:129], off offset:16
	global_store_dwordx4 v[160:161], v[118:121], off offset:512
	global_store_dwordx4 v[160:161], v[114:117], off offset:528
	v_add_u32_e32 v250, s54, v176
	v_ashrrev_i32_e32 v251, 31, v250
	v_lshlrev_b64 v[250:251], 10, v[250:251]
	v_lshl_add_u64 v[250:251], v[250:251], 0, v[142:143]
	v_lshlrev_b64 v[250:251], 2, v[250:251]
	v_lshl_add_u64 v[158:159], s[34:35], 0, v[250:251]
	v_lshl_add_u64 v[160:161], s[14:15], 0, v[250:251]
	ds_read_b32 v156, v186
	global_load_dwordx4 v[234:237], v[158:159], off offset:16
	global_load_dwordx4 v[238:241], v[158:159], off
	global_load_dwordx4 v[146:149], v[158:159], off offset:528
	global_load_dwordx4 v[150:153], v[158:159], off offset:512
	s_waitcnt lgkmcnt(1)
	v_pk_mul_f32 v[94:95], v[94:95], v[154:155] op_sel_hi:[1,0]
	v_pk_mul_f32 v[96:97], v[96:97], v[154:155] op_sel_hi:[1,0]
	v_pk_mul_f32 v[90:91], v[90:91], v[154:155] op_sel_hi:[1,0]
	v_pk_mul_f32 v[92:93], v[92:93], v[154:155] op_sel_hi:[1,0]
	v_pk_mul_f32 v[78:79], v[78:79], v[154:155] op_sel_hi:[1,0]
	v_pk_mul_f32 v[80:81], v[80:81], v[154:155] op_sel_hi:[1,0]
	v_pk_mul_f32 v[74:75], v[74:75], v[154:155] op_sel_hi:[1,0]
	v_pk_mul_f32 v[76:77], v[76:77], v[154:155] op_sel_hi:[1,0]
	s_waitcnt vmcnt(8)
;     __device__ __forceinline__ void operator()(f32x4 (&acc)[2][2][4][2], const Unit& u, int wr, int wc, int fr, int fq) const {
;     ...
; #pragma unroll
;         for (int ai = 0; ai < 2; ++ai)
; #pragma unroll
;             for (int m = 0; m < 4; ++m) { const int rl = ai * 128 + wr * 64 + m * 16 + fr; const float r1 = S[rl]; const size_t off = (size_t)(u.pm * 256 + rl) * DM + col0;
; #pragma unroll
;                 for (int bj = 0; bj < 2; ++bj) { const f32x4 xa = *(const f32x4*)(xin + off + bj * 128), xb = *(const f32x4*)(xin + off + bj * 128 + 4);
;                     const f32x4 ga = *(const f32x4*)(gpost + col0 + bj * 128), gb = *(const f32x4*)(gpost + col0 + bj * 128 + 4);
;                     const f32x4 v0 = xa + acc[ai][bj][m][0] * r1 * ga, v1 = xb + acc[ai][bj][m][1] * r1 * gb;
;                     *(f32x4*)(xout + off + bj * 128) = v0; *(f32x4*)(xout + off + bj * 128 + 4) = v1; acc[ai][bj][m][0] = v0; acc[ai][bj][m][1] = v1; }
;                 asm volatile("" ::: "memory"); }
;         if (gnext) {
;             exchange(acc, u, 1, wr, wc, fr, fq);
	v_pk_fma_f32 v[90:91], v[90:91], v[222:223], v[202:203]
	v_pk_fma_f32 v[92:93], v[92:93], v[224:225], v[204:205]
	v_pk_fma_f32 v[94:95], v[94:95], v[218:219], v[206:207]
	v_pk_fma_f32 v[96:97], v[96:97], v[220:221], v[208:209]
	v_pk_fma_f32 v[74:75], v[74:75], v[230:231], v[210:211]
	v_pk_fma_f32 v[76:77], v[76:77], v[232:233], v[212:213]
	v_pk_fma_f32 v[78:79], v[78:79], v[226:227], v[214:215]
	v_pk_fma_f32 v[80:81], v[80:81], v[228:229], v[216:217]
	global_store_dwordx4 v[162:163], v[94:97], off
	global_store_dwordx4 v[162:163], v[90:93], off offset:16
	global_store_dwordx4 v[162:163], v[78:81], off offset:512
	global_store_dwordx4 v[162:163], v[74:77], off offset:528
	v_add_u32_e32 v250, s54, v177
	v_ashrrev_i32_e32 v251, 31, v250
	v_lshlrev_b64 v[250:251], 10, v[250:251]
	v_lshl_add_u64 v[250:251], v[250:251], 0, v[142:143]
	v_lshlrev_b64 v[250:251], 2, v[250:251]
	v_lshl_add_u64 v[164:165], s[34:35], 0, v[250:251]
	v_lshl_add_u64 v[162:163], s[14:15], 0, v[250:251]
	ds_read_b32 v154, v187
	global_load_dwordx4 v[202:205], v[164:165], off offset:16
	global_load_dwordx4 v[206:209], v[164:165], off
	global_load_dwordx4 v[210:213], v[164:165], off offset:528
	global_load_dwordx4 v[214:217], v[164:165], off offset:512
	s_waitcnt lgkmcnt(1)
	v_pk_mul_f32 v[54:55], v[54:55], v[156:157] op_sel_hi:[1,0]
	v_pk_mul_f32 v[56:57], v[56:57], v[156:157] op_sel_hi:[1,0]
	v_pk_mul_f32 v[50:51], v[50:51], v[156:157] op_sel_hi:[1,0]
	v_pk_mul_f32 v[52:53], v[52:53], v[156:157] op_sel_hi:[1,0]
	v_pk_mul_f32 v[38:39], v[38:39], v[156:157] op_sel_hi:[1,0]
	v_pk_mul_f32 v[40:41], v[40:41], v[156:157] op_sel_hi:[1,0]
	v_pk_mul_f32 v[34:35], v[34:35], v[156:157] op_sel_hi:[1,0]
	v_pk_mul_f32 v[36:37], v[36:37], v[156:157] op_sel_hi:[1,0]
	s_waitcnt vmcnt(8)
	v_pk_fma_f32 v[50:51], v[50:51], v[222:223], v[234:235]
	v_pk_fma_f32 v[52:53], v[52:53], v[224:225], v[236:237]
	v_pk_fma_f32 v[54:55], v[54:55], v[218:219], v[238:239]
	v_pk_fma_f32 v[56:57], v[56:57], v[220:221], v[240:241]
	v_pk_fma_f32 v[34:35], v[34:35], v[230:231], v[146:147]
	v_pk_fma_f32 v[36:37], v[36:37], v[232:233], v[148:149]
	v_pk_fma_f32 v[38:39], v[38:39], v[226:227], v[150:151]
	v_pk_fma_f32 v[40:41], v[40:41], v[228:229], v[152:153]
	global_store_dwordx4 v[160:161], v[54:57], off
	global_store_dwordx4 v[160:161], v[50:53], off offset:16
	global_store_dwordx4 v[160:161], v[38:41], off offset:512
	global_store_dwordx4 v[160:161], v[34:37], off offset:528
	v_add_u32_e32 v250, s54, v178
	v_ashrrev_i32_e32 v251, 31, v250
	v_lshlrev_b64 v[250:251], 10, v[250:251]
	v_lshl_add_u64 v[250:251], v[250:251], 0, v[142:143]
	v_lshlrev_b64 v[250:251], 2, v[250:251]
	v_lshl_add_u64 v[158:159], s[34:35], 0, v[250:251]
	v_lshl_add_u64 v[160:161], s[14:15], 0, v[250:251]
	ds_read_b32 v156, v188
	global_load_dwordx4 v[234:237], v[158:159], off offset:16
	global_load_dwordx4 v[238:241], v[158:159], off
	global_load_dwordx4 v[146:149], v[158:159], off offset:528
	global_load_dwordx4 v[150:153], v[158:159], off offset:512
	s_waitcnt lgkmcnt(1)
	v_pk_mul_f32 v[30:31], v[30:31], v[154:155] op_sel_hi:[1,0]
	v_pk_mul_f32 v[32:33], v[32:33], v[154:155] op_sel_hi:[1,0]
	v_pk_mul_f32 v[26:27], v[26:27], v[154:155] op_sel_hi:[1,0]
	v_pk_mul_f32 v[28:29], v[28:29], v[154:155] op_sel_hi:[1,0]
	v_pk_mul_f32 v[22:23], v[22:23], v[154:155] op_sel_hi:[1,0]
	v_pk_mul_f32 v[24:25], v[24:25], v[154:155] op_sel_hi:[1,0]
	v_pk_mul_f32 v[18:19], v[18:19], v[154:155] op_sel_hi:[1,0]
	v_pk_mul_f32 v[20:21], v[20:21], v[154:155] op_sel_hi:[1,0]
	s_waitcnt vmcnt(8)
	v_pk_fma_f32 v[26:27], v[26:27], v[222:223], v[202:203]
	v_pk_fma_f32 v[28:29], v[28:29], v[224:225], v[204:205]
	v_pk_fma_f32 v[30:31], v[30:31], v[218:219], v[206:207]
	v_pk_fma_f32 v[32:33], v[32:33], v[220:221], v[208:209]
	v_pk_fma_f32 v[18:19], v[18:19], v[230:231], v[210:211]
	v_pk_fma_f32 v[20:21], v[20:21], v[232:233], v[212:213]
	v_pk_fma_f32 v[22:23], v[22:23], v[226:227], v[214:215]
	v_pk_fma_f32 v[24:25], v[24:25], v[228:229], v[216:217]
	global_store_dwordx4 v[162:163], v[30:33], off
	global_store_dwordx4 v[162:163], v[26:29], off offset:16
	global_store_dwordx4 v[162:163], v[22:25], off offset:512
	global_store_dwordx4 v[162:163], v[18:21], off offset:528
	s_waitcnt lgkmcnt(0)
	v_pk_mul_f32 v[14:15], v[14:15], v[156:157] op_sel_hi:[1,0]
	v_pk_mul_f32 v[16:17], v[16:17], v[156:157] op_sel_hi:[1,0]
	v_pk_mul_f32 v[10:11], v[10:11], v[156:157] op_sel_hi:[1,0]
	v_pk_mul_f32 v[12:13], v[12:13], v[156:157] op_sel_hi:[1,0]
	v_pk_mul_f32 v[6:7], v[6:7], v[156:157] op_sel_hi:[1,0]
	v_pk_mul_f32 v[8:9], v[8:9], v[156:157] op_sel_hi:[1,0]
	v_pk_mul_f32 v[2:3], v[2:3], v[156:157] op_sel_hi:[1,0]
	v_pk_mul_f32 v[4:5], v[4:5], v[156:157] op_sel_hi:[1,0]
	s_waitcnt vmcnt(4)
	v_pk_fma_f32 v[10:11], v[10:11], v[222:223], v[234:235]
	v_pk_fma_f32 v[12:13], v[12:13], v[224:225], v[236:237]
	v_pk_fma_f32 v[14:15], v[14:15], v[218:219], v[238:239]
	v_pk_fma_f32 v[16:17], v[16:17], v[220:221], v[240:241]
	v_pk_fma_f32 v[2:3], v[2:3], v[230:231], v[146:147]
	v_pk_fma_f32 v[4:5], v[4:5], v[232:233], v[148:149]
	v_pk_fma_f32 v[6:7], v[6:7], v[226:227], v[150:151]
	v_pk_fma_f32 v[8:9], v[8:9], v[228:229], v[152:153]
	global_store_dwordx4 v[160:161], v[14:17], off
	global_store_dwordx4 v[160:161], v[10:13], off offset:16
	global_store_dwordx4 v[160:161], v[6:9], off offset:512
	global_store_dwordx4 v[160:161], v[2:5], off offset:528
	v_add_u32_e32 v146, s54, v172
	v_ashrrev_i32_e32 v147, 31, v146
	v_add_u32_e32 v148, s54, v173
	v_ashrrev_i32_e32 v149, 31, v148
	v_add_u32_e32 v150, s54, v174
	v_ashrrev_i32_e32 v151, 31, v150
	v_add_u32_e32 v152, s54, v175
	v_ashrrev_i32_e32 v153, 31, v152
	v_add_u32_e32 v156, s54, v176
	v_ashrrev_i32_e32 v157, 31, v156
	v_add_u32_e32 v158, s54, v177
	v_ashrrev_i32_e32 v159, 31, v158
	v_add_u32_e32 v166, s54, v178
	v_ashrrev_i32_e32 v167, 31, v166
	s_cbranch_vccnz .LBB0_272
; __device__ __forceinline__ float swap_add(float v) { auto rr = __builtin_amdgcn_permlane32_swap(__float_as_uint(v), __float_as_uint(v), false, false); return __uint_as_float(rr[0]) + __uint_as_float(rr[1]); }
;     __device__ __forceinline__ void exchange(const f32x4 (&acc)[2][2][4][2], const Unit& u, int e, int wr, int wc, int fr, int fq) const {
;     ...
; #pragma unroll
;         for (int ai = 0; ai < 2; ++ai)
; #pragma unroll
;             for (int m = 0; m < 4; ++m) { float q = 0.f;
; #pragma unroll
;                 for (int bj = 0; bj < 2; ++bj)
; #pragma unroll
;                     for (int n = 0; n < 2; ++n) { const f32x4 v = acc[ai][bj][m][n]; q += (v[0] * v[0] + v[1] * v[1]) + (v[2] * v[2] + v[3] * v[3]); }
;                 q += __int_as_float(__builtin_amdgcn_ds_bpermute((lid ^ 16) << 2, __float_as_int(q))); q = swap_add(q);
;                 if (fq == 0) P[(ai * 128 + wr * 64 + m * 16 + fr) * 4 + wc] = q; }
	v_mul_f32_e32 v154, v43, v43
	v_mul_f32_e32 v155, v45, v45
	v_fmac_f32_e32 v154, v42, v42
	v_fmac_f32_e32 v155, v44, v44
	v_add_f32_e32 v154, v154, v155
	v_mul_f32_e32 v155, v47, v47
	v_mul_f32_e32 v160, v49, v49
	v_fmac_f32_e32 v155, v46, v46
	v_fmac_f32_e32 v160, v48, v48
	v_add_f32_e32 v155, v155, v160
	v_add_f32_e32 v154, v154, v155
	v_mul_f32_e32 v155, v63, v63
	v_mul_f32_e32 v160, v65, v65
	v_fmac_f32_e32 v155, v62, v62
	v_fmac_f32_e32 v160, v64, v64
	v_add_f32_e32 v155, v155, v160
	v_add_f32_e32 v154, v154, v155
	v_mul_f32_e32 v155, v59, v59
	v_mul_f32_e32 v160, v61, v61
	v_fmac_f32_e32 v155, v58, v58
	v_fmac_f32_e32 v160, v60, v60
	v_add_f32_e32 v155, v155, v160
	v_add_f32_e32 v154, v154, v155
	ds_bpermute_b32 v155, v171, v154
	s_waitcnt lgkmcnt(0)
	v_add_f32_e32 v154, v154, v155
	v_mov_b32_e32 v155, v154
	s_nop 1
	v_permlane32_swap_b32_e32 v154, v155
	s_and_saveexec_b64 s[54:55], s[42:43]
	v_add_f32_e32 v154, v154, v155
	ds_write_b32 v191, v154
	s_or_b64 exec, exec, s[54:55]
	v_mul_f32_e32 v154, v67, v67
	v_mul_f32_e32 v155, v69, v69
	v_fmac_f32_e32 v154, v66, v66
	v_fmac_f32_e32 v155, v68, v68
	v_add_f32_e32 v154, v154, v155
	v_mul_f32_e32 v155, v71, v71
	v_mul_f32_e32 v160, v73, v73
	v_fmac_f32_e32 v155, v70, v70
	v_fmac_f32_e32 v160, v72, v72
	v_add_f32_e32 v155, v155, v160
	v_add_f32_e32 v154, v154, v155
	v_mul_f32_e32 v155, v87, v87
	v_mul_f32_e32 v160, v89, v89
	v_fmac_f32_e32 v155, v86, v86
	v_fmac_f32_e32 v160, v88, v88
	v_add_f32_e32 v155, v155, v160
	v_add_f32_e32 v154, v154, v155
	v_mul_f32_e32 v155, v83, v83
	v_mul_f32_e32 v160, v85, v85
	v_fmac_f32_e32 v155, v82, v82
	v_fmac_f32_e32 v160, v84, v84
	v_add_f32_e32 v155, v155, v160
	v_add_f32_e32 v154, v154, v155
	ds_bpermute_b32 v155, v171, v154
	s_waitcnt lgkmcnt(0)
	v_add_f32_e32 v154, v154, v155
	v_mov_b32_e32 v155, v154
	s_nop 1
	v_permlane32_swap_b32_e32 v154, v155
	s_and_saveexec_b64 s[54:55], s[42:43]
	v_add_f32_e32 v154, v154, v155
	ds_write_b32 v191, v154 offset:256
	s_or_b64 exec, exec, s[54:55]
	v_mul_f32_e32 v154, v99, v99
	v_mul_f32_e32 v155, v101, v101
	v_fmac_f32_e32 v154, v98, v98
	v_fmac_f32_e32 v155, v100, v100
	v_add_f32_e32 v154, v154, v155
	v_mul_f32_e32 v155, v103, v103
	v_mul_f32_e32 v160, v105, v105
	v_fmac_f32_e32 v155, v102, v102
	v_fmac_f32_e32 v160, v104, v104
	v_add_f32_e32 v155, v155, v160
	v_add_f32_e32 v154, v154, v155
	v_mul_f32_e32 v155, v111, v111
	v_mul_f32_e32 v160, v113, v113
	v_fmac_f32_e32 v155, v110, v110
	v_fmac_f32_e32 v160, v112, v112
	v_add_f32_e32 v155, v155, v160
	v_add_f32_e32 v154, v154, v155
	v_mul_f32_e32 v155, v107, v107
	v_mul_f32_e32 v160, v109, v109
	v_fmac_f32_e32 v155, v106, v106
	v_fmac_f32_e32 v160, v108, v108
	v_add_f32_e32 v155, v155, v160
	v_add_f32_e32 v154, v154, v155
	ds_bpermute_b32 v155, v171, v154
	s_waitcnt lgkmcnt(0)
	v_add_f32_e32 v154, v154, v155
	v_mov_b32_e32 v155, v154
	s_nop 1
	v_permlane32_swap_b32_e32 v154, v155
	s_and_saveexec_b64 s[54:55], s[42:43]
	v_add_f32_e32 v154, v154, v155
	ds_write_b32 v191, v154 offset:512
	s_or_b64 exec, exec, s[54:55]
	v_mul_f32_e32 v154, v123, v123
	v_mul_f32_e32 v155, v125, v125
	v_fmac_f32_e32 v154, v122, v122
	v_fmac_f32_e32 v155, v124, v124
	v_add_f32_e32 v154, v154, v155
	v_mul_f32_e32 v155, v127, v127
	v_mul_f32_e32 v160, v129, v129
	v_fmac_f32_e32 v155, v126, v126
	v_fmac_f32_e32 v160, v128, v128
	v_add_f32_e32 v155, v155, v160
	v_add_f32_e32 v154, v154, v155
	v_mul_f32_e32 v155, v119, v119
	v_mul_f32_e32 v160, v121, v121
	v_fmac_f32_e32 v155, v118, v118
	v_fmac_f32_e32 v160, v120, v120
	v_add_f32_e32 v155, v155, v160
	v_add_f32_e32 v154, v154, v155
	v_mul_f32_e32 v155, v115, v115
	v_mul_f32_e32 v160, v117, v117
	v_fmac_f32_e32 v155, v114, v114
	v_fmac_f32_e32 v160, v116, v116
	v_add_f32_e32 v155, v155, v160
	v_add_f32_e32 v154, v154, v155
	ds_bpermute_b32 v155, v171, v154
	s_waitcnt lgkmcnt(0)
	v_add_f32_e32 v154, v154, v155
	v_mov_b32_e32 v155, v154
	s_nop 1
	v_permlane32_swap_b32_e32 v154, v155
	s_and_saveexec_b64 s[54:55], s[42:43]
	v_add_f32_e32 v154, v154, v155
	ds_write_b32 v191, v154 offset:768
	s_or_b64 exec, exec, s[54:55]
	v_mul_f32_e32 v154, v95, v95
	v_mul_f32_e32 v155, v97, v97
	v_fmac_f32_e32 v154, v94, v94
	v_fmac_f32_e32 v155, v96, v96
	v_add_f32_e32 v154, v154, v155
	v_mul_f32_e32 v155, v91, v91
	v_mul_f32_e32 v160, v93, v93
	v_fmac_f32_e32 v155, v90, v90
	v_fmac_f32_e32 v160, v92, v92
	v_add_f32_e32 v155, v155, v160
	v_add_f32_e32 v154, v154, v155
	v_mul_f32_e32 v155, v79, v79
	v_mul_f32_e32 v160, v81, v81
	v_fmac_f32_e32 v155, v78, v78
	v_fmac_f32_e32 v160, v80, v80
	v_add_f32_e32 v155, v155, v160
	v_add_f32_e32 v154, v154, v155
	v_mul_f32_e32 v155, v75, v75
	v_mul_f32_e32 v160, v77, v77
	v_fmac_f32_e32 v155, v74, v74
	v_fmac_f32_e32 v160, v76, v76
	v_add_f32_e32 v155, v155, v160
	v_add_f32_e32 v154, v154, v155
	ds_bpermute_b32 v155, v171, v154
	s_waitcnt lgkmcnt(0)
; __device__ __forceinline__ float swap_add(float v) { auto rr = __builtin_amdgcn_permlane32_swap(__float_as_uint(v), __float_as_uint(v), false, false); return __uint_as_float(rr[0]) + __uint_as_float(rr[1]); }
;     __device__ __forceinline__ void exchange(const f32x4 (&acc)[2][2][4][2], const Unit& u, int e, int wr, int wc, int fr, int fq) const {
;     ...
;         for (int ai = 0; ai < 2; ++ai)
; #pragma unroll
;             for (int m = 0; m < 4; ++m) { float q = 0.f;
; #pragma unroll
;                 for (int bj = 0; bj < 2; ++bj)
; #pragma unroll
;                     for (int n = 0; n < 2; ++n) { const f32x4 v = acc[ai][bj][m][n]; q += (v[0] * v[0] + v[1] * v[1]) + (v[2] * v[2] + v[3] * v[3]); }
;                 q += __int_as_float(__builtin_amdgcn_ds_bpermute((lid ^ 16) << 2, __float_as_int(q))); q = swap_add(q);
;                 if (fq == 0) P[(ai * 128 + wr * 64 + m * 16 + fr) * 4 + wc] = q; }
;         __syncthreads();
;         float* xb = xbuf + (size_t)e * T * 4 + (size_t)u.pm * 256 * 4; unsigned* c = cnt + (e * 64 + u.pm) * 64;
;         if (tid < 256) { const float tot = (P[tid * 4] + P[tid * 4 + 1]) + (P[tid * 4 + 2] + P[tid * 4 + 3]);
;             __hip_atomic_store(xb + tid * 4 + u.pn, tot, __ATOMIC_RELAXED, __HIP_MEMORY_SCOPE_AGENT); }
	v_add_f32_e32 v154, v154, v155
	v_mov_b32_e32 v155, v154
	s_nop 1
	v_permlane32_swap_b32_e32 v154, v155
	s_and_saveexec_b64 s[54:55], s[42:43]
	v_add_f32_e32 v154, v154, v155
	ds_write_b32 v191, v154 offset:2048
	s_or_b64 exec, exec, s[54:55]
	v_mul_f32_e32 v154, v55, v55
	v_mul_f32_e32 v155, v57, v57
	v_fmac_f32_e32 v154, v54, v54
	v_fmac_f32_e32 v155, v56, v56
	v_add_f32_e32 v154, v154, v155
	v_mul_f32_e32 v155, v51, v51
	v_mul_f32_e32 v160, v53, v53
	v_fmac_f32_e32 v155, v50, v50
	v_fmac_f32_e32 v160, v52, v52
	v_add_f32_e32 v155, v155, v160
	v_add_f32_e32 v154, v154, v155
	v_mul_f32_e32 v155, v39, v39
	v_mul_f32_e32 v160, v41, v41
	v_fmac_f32_e32 v155, v38, v38
	v_fmac_f32_e32 v160, v40, v40
	v_add_f32_e32 v155, v155, v160
	v_add_f32_e32 v154, v154, v155
	v_mul_f32_e32 v155, v35, v35
	v_mul_f32_e32 v160, v37, v37
	v_fmac_f32_e32 v155, v34, v34
	v_fmac_f32_e32 v160, v36, v36
	v_add_f32_e32 v155, v155, v160
	v_add_f32_e32 v154, v154, v155
	ds_bpermute_b32 v155, v171, v154
	s_waitcnt lgkmcnt(0)
	v_add_f32_e32 v154, v154, v155
	v_mov_b32_e32 v155, v154
	s_nop 1
	v_permlane32_swap_b32_e32 v154, v155
	s_and_saveexec_b64 s[54:55], s[42:43]
	v_add_f32_e32 v154, v154, v155
	ds_write_b32 v191, v154 offset:2304
	s_or_b64 exec, exec, s[54:55]
	v_mul_f32_e32 v154, v31, v31
	v_mul_f32_e32 v155, v33, v33
	v_fmac_f32_e32 v154, v30, v30
	v_fmac_f32_e32 v155, v32, v32
	v_add_f32_e32 v154, v154, v155
	v_mul_f32_e32 v155, v27, v27
	v_mul_f32_e32 v160, v29, v29
	v_fmac_f32_e32 v155, v26, v26
	v_fmac_f32_e32 v160, v28, v28
	v_add_f32_e32 v155, v155, v160
	v_add_f32_e32 v154, v154, v155
	v_mul_f32_e32 v155, v23, v23
	v_mul_f32_e32 v160, v25, v25
	v_fmac_f32_e32 v155, v22, v22
	v_fmac_f32_e32 v160, v24, v24
	v_add_f32_e32 v155, v155, v160
	v_add_f32_e32 v154, v154, v155
	v_mul_f32_e32 v155, v19, v19
	v_mul_f32_e32 v160, v21, v21
	v_fmac_f32_e32 v155, v18, v18
	v_fmac_f32_e32 v160, v20, v20
	v_add_f32_e32 v155, v155, v160
	v_add_f32_e32 v154, v154, v155
	ds_bpermute_b32 v155, v171, v154
	s_waitcnt lgkmcnt(0)
	v_add_f32_e32 v154, v154, v155
	v_mov_b32_e32 v155, v154
	s_nop 1
	v_permlane32_swap_b32_e32 v154, v155
	s_and_saveexec_b64 s[54:55], s[42:43]
	v_add_f32_e32 v154, v154, v155
	ds_write_b32 v191, v154 offset:2560
	s_or_b64 exec, exec, s[54:55]
	v_mul_f32_e32 v154, v15, v15
	v_mul_f32_e32 v155, v17, v17
	v_fmac_f32_e32 v154, v14, v14
	v_fmac_f32_e32 v155, v16, v16
	v_add_f32_e32 v154, v154, v155
	v_mul_f32_e32 v155, v11, v11
	v_mul_f32_e32 v160, v13, v13
	v_fmac_f32_e32 v155, v10, v10
	v_fmac_f32_e32 v160, v12, v12
	v_add_f32_e32 v155, v155, v160
	v_add_f32_e32 v154, v154, v155
	v_mul_f32_e32 v155, v7, v7
	v_mul_f32_e32 v160, v9, v9
	v_fmac_f32_e32 v155, v6, v6
	v_fmac_f32_e32 v160, v8, v8
	v_add_f32_e32 v155, v155, v160
	v_add_f32_e32 v154, v154, v155
	v_mul_f32_e32 v155, v3, v3
	v_mul_f32_e32 v160, v5, v5
	v_fmac_f32_e32 v155, v2, v2
	v_fmac_f32_e32 v160, v4, v4
	v_add_f32_e32 v155, v155, v160
	v_add_f32_e32 v154, v154, v155
	ds_bpermute_b32 v155, v171, v154
	s_waitcnt lgkmcnt(0)
	v_add_f32_e32 v154, v154, v155
	v_mov_b32_e32 v155, v154
	s_nop 1
	v_permlane32_swap_b32_e32 v154, v155
	s_and_saveexec_b64 s[54:55], s[42:43]
	v_add_f32_e32 v154, v154, v155
	ds_write_b32 v191, v154 offset:2816
	s_or_b64 exec, exec, s[54:55]
	s_add_u32 s12, s97, s12
	s_addc_u32 s13, s72, s13
	v_lshl_add_u64 v[154:155], v[136:137], 0, s[12:13]
	s_waitcnt lgkmcnt(0)
	s_barrier
	s_and_saveexec_b64 s[12:13], s[44:45]
	s_cbranch_execz .LBB0_254
	ds_read_b128 v[202:205], v179
	s_ashr_i32 s77, s76, 31
	v_lshl_add_u64 v[162:163], s[76:77], 4, 0
	v_lshl_add_u64 v[162:163], v[162:163], 4, 0
	v_lshl_add_u64 v[162:163], v[162:163], 2, v[154:155]
	s_waitcnt lgkmcnt(0)
	v_mov_b32_e32 v160, v203
	v_mov_b32_e32 v161, v204
	v_mov_b32_e32 v203, v205
	v_pk_add_f32 v[160:161], v[160:161], v[202:203]
	s_nop 0
	v_pk_add_f32 v[160:161], v[160:161], v[160:161] op_sel:[0,1] op_sel_hi:[1,0]
	global_store_dword v[162:163], v160, off sc1

;     __device__ __forceinline__ void exchange(const f32x4 (&acc)[2][2][4][2], const Unit& u, int e, int wr, int wc, int fr, int fq) const {
;     ...
;         asm volatile("s_waitcnt vmcnt(0) lgkmcnt(0)" ::: "memory");
;         __syncthreads();
;         if (tid < 256) { float t4 = 0.f;
; #pragma unroll
;             for (int k = 0; k < 4; ++k) t4 += __hip_atomic_load(xb + tid * 4 + k, __ATOMIC_RELAXED, __HIP_MEMORY_SCOPE_AGENT);
;             S[tid] = 1.0f / sqrtf(t4 * (1.f / DM) + EPS); }
.LBB0_269:
	s_waitcnt vmcnt(0) lgkmcnt(0)
	s_waitcnt lgkmcnt(0)
	s_barrier
	s_and_saveexec_b64 s[12:13], s[44:45]
	s_cbranch_execz .LBB0_271
	global_load_dword v160, v[154:155], off sc1
	global_load_dword v161, v[154:155], off offset:1024 sc1
	global_load_dword v162, v[154:155], off offset:2048 sc1
	s_nop 0
	global_load_dword v154, v[154:155], off offset:3072 sc1
	s_mov_b32 s50, 0xf800000
	s_waitcnt vmcnt(3)
	v_add_f32_e32 v155, 0, v160
	s_waitcnt vmcnt(2)
	v_add_f32_e32 v155, v155, v161
	s_waitcnt vmcnt(1)
	v_add_f32_e32 v155, v155, v162
	s_waitcnt vmcnt(0)
	v_add_f32_e32 v154, v155, v154
	v_fmamk_f32 v154, v154, 0x3a800000, v193
	v_mul_f32_e32 v155, 0x4f800000, v154
	v_cmp_gt_f32_e32 vcc, s50, v154
	s_nop 1
	v_cndmask_b32_e32 v154, v154, v155, vcc
	v_sqrt_f32_e32 v155, v154
	s_nop 0
	v_add_u32_e32 v160, -1, v155
	v_add_u32_e32 v161, 1, v155
	v_fma_f32 v162, -v160, v155, v154
	v_fma_f32 v163, -v161, v155, v154
	v_cmp_ge_f32_e64 s[50:51], 0, v162
	s_nop 1
	v_cndmask_b32_e64 v155, v155, v160, s[50:51]
	v_cmp_lt_f32_e64 s[50:51], 0, v163
	s_nop 1
	v_cndmask_b32_e64 v155, v155, v161, s[50:51]
	v_mul_f32_e32 v160, 0x37800000, v155
	v_cndmask_b32_e32 v155, v155, v160, vcc
	v_cmp_class_f32_e32 vcc, v154, v194
	s_nop 1
	v_cndmask_b32_e32 v154, v155, v154, vcc
	v_div_scale_f32 v155, s[50:51], v154, v154, 1.0
	v_rcp_f32_e32 v160, v155
	v_div_scale_f32 v161, vcc, 1.0, v154, 1.0
	v_fma_f32 v162, -v155, v160, 1.0
	v_fmac_f32_e32 v160, v162, v160
	v_mul_f32_e32 v162, v161, v160
	v_fma_f32 v163, -v155, v162, v161
	v_fmac_f32_e32 v162, v163, v160
	v_fma_f32 v155, -v155, v162, v161
	v_div_fmas_f32 v155, v155, v160, v162
	v_div_fixup_f32 v154, v155, v154, 1.0
	ds_write_b32 v180, v154
